# v021 plus the same two-batches-in-flight prefetch in the w_out and FFN2-down residual epilogues
# speedup vs baseline: 1.0162x; 1.0014x over previous
; #define PG8_STAGE(bufoff, gbase, voff) do { _Pragma("unroll") for (int _i = 0; _i < 2; ++_i) \
;         __builtin_amdgcn_global_load_lds((const unsigned*)((const char*)(gbase) + (voff)[_i]), (LAS unsigned*)(lds + (bufoff) + ldsw + _i * 8192), 16, 0, 0); } while (0)
; #define PG8_LDA(dst, b, h) do { _Pragma("unroll") for (int m = 0; m < 4; ++m) _Pragma("unroll") for (int k = 0; k < 2; ++k) dst[m][k] = *(const LAS bf16x8*)(lds + PG8_SA(b, h) + aoff + m * 2048 + k * 1024); } while (0)
; #define PG8_WAIT_V(n) asm volatile("s_waitcnt vmcnt(" #n ")" ::: "memory")
; #define PG8_WAIT_L(n) asm volatile("s_waitcnt lgkmcnt(" #n ")" ::: "memory")
; template <class Epi, class Sched>
; __device__ __forceinline__ void gemm_phase(LAS unsigned char* lds, const Gemm g, const Sched S, const Epi E) {
;     ...
;         for (int t = 0; t < nt; t += 2) {
;             const bool last = (t == nt - 2);
;             const char* a1 = cA + (size_t)(t + 1) * kstep;
;             const char* a2 = last ? nA : cA + (size_t)(t + 2) * kstep; const char* b2 = last ? nB : cB + (size_t)(t + 2) * kstep;
;             const char* a3 = a2 + kstep; const char* b3 = b2 + kstep;
;             PG8_LDB(B0, 0, 0); PG8_SCHED; PG8_LDA(At, 0, 0); PG8_STAGE(PG8_SA(1, 1), a1 + hstep, voffA);
;             PG8_WAIT_L(8); PG8_BAR; PG8_WAIT_L(0); PG8_MMA(0, 0, At, B0); PG8_BAR; PG8_SCHED;
;             PG8_LDB(B1, 0, 1); PG8_STAGE(PG8_SB(0, 0), b2, voffB);
;             PG8_BAR; PG8_WAIT_L(0); PG8_MMA(0, 1, At, B1); PG8_BAR;
;             PG8_LDA(At, 0, 1); PG8_STAGE(PG8_SA(0, 0), a2, voffA);
;             PG8_BAR; PG8_WAIT_L(0); PG8_MMA(1, 0, At, B0); PG8_BAR; PG8_SCHED;
;             PG8_STAGE(PG8_SB(0, 1), b2 + hstep, voffB);
;             PG8_WAIT_V(6); PG8_BAR; PG8_MMA(1, 1, At, B1); PG8_BAR;
;             PG8_LDB(B0, 1, 0); PG8_SCHED; PG8_LDA(At, 1, 0); PG8_STAGE(PG8_SA(0, 1), a2 + hstep, voffA);
;             PG8_WAIT_L(8); PG8_BAR; PG8_WAIT_L(0); PG8_MMA(0, 0, At, B0); PG8_BAR; PG8_SCHED;
;             PG8_LDB(B1, 1, 1); PG8_STAGE(PG8_SB(1, 0), b3, voffB);
;             PG8_BAR; PG8_WAIT_L(0); PG8_MMA(0, 1, At, B1); PG8_BAR;
;             PG8_LDA(At, 1, 1); PG8_STAGE(PG8_SA(1, 0), a3, voffA);
;             PG8_BAR; PG8_WAIT_L(0); PG8_MMA(1, 0, At, B0); PG8_BAR; PG8_SCHED;
;             PG8_STAGE(PG8_SB(1, 1), b3 + hstep, voffB);
;             PG8_WAIT_V(6); PG8_BAR; PG8_MMA(1, 1, At, B1); PG8_BAR;
.LBB0_1330:
	ds_read_b128 v[156:159], v153
	ds_read_b128 v[160:163], v153 offset:1024
	ds_read_b128 v[164:167], v153 offset:2048
	ds_read_b128 v[168:171], v153 offset:3072
	s_add_u32 s22, s20, 0xfff80080
	s_addc_u32 s23, s21, -1
	s_cmp_eq_u32 s43, 28
	s_cselect_b32 s27, s11, s23
	s_cselect_b32 s26, s14, s22
	s_cselect_b32 s23, s9, s42
	s_cselect_b32 s22, s15, s41
	v_lshl_add_u64 v[142:143], s[20:21], 0, v[134:135]
	s_add_i32 m0, s19, 0xc000
	ds_read_b128 v[172:175], v154
	ds_read_b128 v[176:179], v154 offset:1024
	ds_read_b128 v[180:183], v154 offset:2048
	ds_read_b128 v[184:187], v154 offset:3072
	ds_read_b128 v[188:191], v154 offset:4096
	ds_read_b128 v[192:195], v154 offset:5120
	ds_read_b128 v[196:199], v154 offset:6144
	ds_read_b128 v[200:203], v154 offset:7168
	global_load_lds_dwordx4 v[142:143], off
	v_lshl_add_u64 v[142:143], s[20:21], 0, v[136:137]
	s_add_i32 m0, s19, 0xe000
	s_nop 0
	global_load_lds_dwordx4 v[142:143], off
	s_waitcnt lgkmcnt(8)
	s_barrier
	s_waitcnt lgkmcnt(0)
	s_setprio 1
	s_waitcnt lgkmcnt(0)
	v_mfma_f32_16x16x32_bf16 v[126:129], v[156:159], v[172:175], v[126:129]
	v_mfma_f32_16x16x32_bf16 v[122:125], v[164:167], v[172:175], v[122:125]
	v_mfma_f32_16x16x32_bf16 v[110:113], v[156:159], v[180:183], v[110:113]
	v_mfma_f32_16x16x32_bf16 v[106:109], v[164:167], v[180:183], v[106:109]
	v_mfma_f32_16x16x32_bf16 v[98:101], v[156:159], v[188:191], v[98:101]
	v_mfma_f32_16x16x32_bf16 v[90:93], v[164:167], v[188:191], v[90:93]
	v_mfma_f32_16x16x32_bf16 v[82:85], v[156:159], v[196:199], v[82:85]
	v_mfma_f32_16x16x32_bf16 v[74:77], v[164:167], v[196:199], v[74:77]
	v_mfma_f32_16x16x32_bf16 v[126:129], v[160:163], v[176:179], v[126:129]
	v_mfma_f32_16x16x32_bf16 v[122:125], v[168:171], v[176:179], v[122:125]
	v_mfma_f32_16x16x32_bf16 v[110:113], v[160:163], v[184:187], v[110:113]
	v_mfma_f32_16x16x32_bf16 v[106:109], v[168:171], v[184:187], v[106:109]
	v_mfma_f32_16x16x32_bf16 v[98:101], v[160:163], v[192:195], v[98:101]
	v_mfma_f32_16x16x32_bf16 v[90:93], v[168:171], v[192:195], v[90:93]
	v_mfma_f32_16x16x32_bf16 v[82:85], v[160:163], v[200:203], v[82:85]
	s_barrier
	v_mfma_f32_16x16x32_bf16 v[74:77], v[168:171], v[200:203], v[74:77]
	s_setprio 0
	s_add_i32 s44, s39, s24
	v_lshl_add_u64 v[142:143], s[22:23], 0, v[130:131]
	s_mov_b32 m0, s44
	ds_read_b128 v[214:217], v155
	ds_read_b128 v[218:221], v155 offset:1024
	ds_read_b128 v[222:225], v155 offset:2048
	ds_read_b128 v[226:229], v155 offset:3072
	global_load_lds_dwordx4 v[142:143], off
	v_lshl_add_u64 v[206:207], s[22:23], 0, v[132:133]
	s_add_i32 m0, s44, 0x2000
	s_nop 0
	global_load_lds_dwordx4 v[206:207], off
	s_barrier
	s_waitcnt lgkmcnt(0)
	s_setprio 1
	s_waitcnt lgkmcnt(0)
	v_mfma_f32_16x16x32_bf16 v[118:121], v[214:217], v[172:175], v[118:121]
	v_mfma_f32_16x16x32_bf16 v[114:117], v[222:225], v[172:175], v[114:117]
	v_mfma_f32_16x16x32_bf16 v[102:105], v[214:217], v[180:183], v[102:105]
	v_mfma_f32_16x16x32_bf16 v[94:97], v[222:225], v[180:183], v[94:97]
	v_mfma_f32_16x16x32_bf16 v[86:89], v[214:217], v[188:191], v[86:89]
	v_mfma_f32_16x16x32_bf16 v[78:81], v[222:225], v[188:191], v[78:81]
	v_mfma_f32_16x16x32_bf16 v[70:73], v[214:217], v[196:199], v[70:73]
	v_mfma_f32_16x16x32_bf16 v[66:69], v[222:225], v[196:199], v[66:69]
	v_mfma_f32_16x16x32_bf16 v[118:121], v[218:221], v[176:179], v[118:121]
	v_mfma_f32_16x16x32_bf16 v[114:117], v[226:229], v[176:179], v[114:117]
	v_mfma_f32_16x16x32_bf16 v[102:105], v[218:221], v[184:187], v[102:105]
	v_mfma_f32_16x16x32_bf16 v[94:97], v[226:229], v[184:187], v[94:97]
	v_mfma_f32_16x16x32_bf16 v[86:89], v[218:221], v[192:195], v[86:89]
	v_mfma_f32_16x16x32_bf16 v[78:81], v[226:229], v[192:195], v[78:81]
	v_mfma_f32_16x16x32_bf16 v[70:73], v[218:221], v[200:203], v[70:73]
	s_barrier
	v_mfma_f32_16x16x32_bf16 v[66:69], v[226:229], v[200:203], v[66:69]
	s_setprio 0
	s_mov_b32 m0, s19
	v_lshl_add_u64 v[230:231], s[26:27], 0, v[130:131]
	ds_read_b128 v[172:175], v154 offset:16384
	ds_read_b128 v[176:179], v154 offset:17408
	ds_read_b128 v[180:183], v154 offset:18432
	ds_read_b128 v[184:187], v154 offset:19456
	ds_read_b128 v[188:191], v154 offset:20480
	ds_read_b128 v[192:195], v154 offset:21504
	ds_read_b128 v[196:199], v154 offset:22528
	ds_read_b128 v[200:203], v154 offset:23552
	global_load_lds_dwordx4 v[230:231], off
	v_lshl_add_u64 v[232:233], s[26:27], 0, v[132:133]
	s_mov_b32 m0, s25
	s_nop 0
	global_load_lds_dwordx4 v[232:233], off
	s_barrier
	s_waitcnt lgkmcnt(0)
	s_setprio 1
	s_waitcnt lgkmcnt(0)
	v_mfma_f32_16x16x32_bf16 v[62:65], v[156:159], v[172:175], v[62:65]
	v_mfma_f32_16x16x32_bf16 v[58:61], v[164:167], v[172:175], v[58:61]
	v_mfma_f32_16x16x32_bf16 v[50:53], v[156:159], v[180:183], v[50:53]
	v_mfma_f32_16x16x32_bf16 v[42:45], v[164:167], v[180:183], v[42:45]
	v_mfma_f32_16x16x32_bf16 v[34:37], v[156:159], v[188:191], v[34:37]
	v_mfma_f32_16x16x32_bf16 v[26:29], v[164:167], v[188:191], v[26:29]
	v_mfma_f32_16x16x32_bf16 v[18:21], v[156:159], v[196:199], v[18:21]
	v_mfma_f32_16x16x32_bf16 v[10:13], v[164:167], v[196:199], v[10:13]
	v_mfma_f32_16x16x32_bf16 v[62:65], v[160:163], v[176:179], v[62:65]
	v_mfma_f32_16x16x32_bf16 v[58:61], v[168:171], v[176:179], v[58:61]
	v_mfma_f32_16x16x32_bf16 v[50:53], v[160:163], v[184:187], v[50:53]
	v_mfma_f32_16x16x32_bf16 v[42:45], v[168:171], v[184:187], v[42:45]
	v_mfma_f32_16x16x32_bf16 v[34:37], v[160:163], v[192:195], v[34:37]
	v_mfma_f32_16x16x32_bf16 v[26:29], v[168:171], v[192:195], v[26:29]
	v_mfma_f32_16x16x32_bf16 v[18:21], v[160:163], v[200:203], v[18:21]
	s_barrier
; #define PG8_STAGE(bufoff, gbase, voff) do { _Pragma("unroll") for (int _i = 0; _i < 2; ++_i) \
;         __builtin_amdgcn_global_load_lds((const unsigned*)((const char*)(gbase) + (voff)[_i]), (LAS unsigned*)(lds + (bufoff) + ldsw + _i * 8192), 16, 0, 0); } while (0)
; #define PG8_LDA(dst, b, h) do { _Pragma("unroll") for (int m = 0; m < 4; ++m) _Pragma("unroll") for (int k = 0; k < 2; ++k) dst[m][k] = *(const LAS bf16x8*)(lds + PG8_SA(b, h) + aoff + m * 2048 + k * 1024); } while (0)
; #define PG8_LDB(dst, b, h) do { _Pragma("unroll") for (int n = 0; n < 2; ++n) _Pragma("unroll") for (int k = 0; k < 2; ++k) dst[n][k] = *(const LAS bf16x8*)(lds + PG8_SB(b, h) + boff + n * 2048 + k * 1024); } while (0)
; #define PG8_WAIT_V(n) asm volatile("s_waitcnt vmcnt(" #n ")" ::: "memory")
; #define PG8_WAIT_L(n) asm volatile("s_waitcnt lgkmcnt(" #n ")" ::: "memory")
; #define PG8_BAR __builtin_amdgcn_s_barrier()
; #define PG8_SCHED __builtin_amdgcn_sched_barrier(0)
; template <class Epi, class Sched>
; __device__ __forceinline__ void gemm_phase(LAS unsigned char* lds, const Gemm g, const Sched S, const Epi E) {
;     ...
;             PG8_LDB(B0, 0, 0); PG8_SCHED; PG8_LDA(At, 0, 0); PG8_STAGE(PG8_SA(1, 1), a1 + hstep, voffA);
;             PG8_WAIT_L(8); PG8_BAR; PG8_WAIT_L(0); PG8_MMA(0, 0, At, B0); PG8_BAR; PG8_SCHED;
;             PG8_LDB(B1, 0, 1); PG8_STAGE(PG8_SB(0, 0), b2, voffB);
;             PG8_BAR; PG8_WAIT_L(0); PG8_MMA(0, 1, At, B1); PG8_BAR;
;             PG8_LDA(At, 0, 1); PG8_STAGE(PG8_SA(0, 0), a2, voffA);
;             PG8_BAR; PG8_WAIT_L(0); PG8_MMA(1, 0, At, B0); PG8_BAR; PG8_SCHED;
;             PG8_STAGE(PG8_SB(0, 1), b2 + hstep, voffB);
;             PG8_WAIT_V(6); PG8_BAR; PG8_MMA(1, 1, At, B1); PG8_BAR;
;             PG8_LDB(B0, 1, 0); PG8_SCHED; PG8_LDA(At, 1, 0); PG8_STAGE(PG8_SA(0, 1), a2 + hstep, voffA);
;             PG8_WAIT_L(8); PG8_BAR; PG8_WAIT_L(0); PG8_MMA(0, 0, At, B0); PG8_BAR; PG8_SCHED;
;             PG8_LDB(B1, 1, 1); PG8_STAGE(PG8_SB(1, 0), b3, voffB);
;             PG8_BAR; PG8_WAIT_L(0); PG8_MMA(0, 1, At, B1); PG8_BAR;
;             PG8_LDA(At, 1, 1); PG8_STAGE(PG8_SA(1, 0), a3, voffA);
;             PG8_BAR; PG8_WAIT_L(0); PG8_MMA(1, 0, At, B0); PG8_BAR; PG8_SCHED;
;             PG8_STAGE(PG8_SB(1, 1), b3 + hstep, voffB);
;             PG8_WAIT_V(6); PG8_BAR; PG8_MMA(1, 1, At, B1); PG8_BAR;
	v_mfma_f32_16x16x32_bf16 v[10:13], v[168:171], v[200:203], v[10:13]
	s_setprio 0
	s_add_u32 s44, s22, 0x80000
	s_addc_u32 s45, s23, 0
	s_add_i32 s46, s40, s24
	v_lshl_add_u64 v[156:157], s[44:45], 0, v[130:131]
	s_mov_b32 m0, s46
	s_nop 0
	global_load_lds_dwordx4 v[156:157], off
	v_lshl_add_u64 v[156:157], s[44:45], 0, v[132:133]
	s_add_i32 m0, s46, 0x2000
	s_nop 0
	global_load_lds_dwordx4 v[156:157], off
	s_waitcnt vmcnt(6)
	s_barrier
	s_setprio 1
	v_mfma_f32_16x16x32_bf16 v[54:57], v[214:217], v[172:175], v[54:57]
	v_mfma_f32_16x16x32_bf16 v[46:49], v[222:225], v[172:175], v[46:49]
	v_mfma_f32_16x16x32_bf16 v[38:41], v[214:217], v[180:183], v[38:41]
	v_mfma_f32_16x16x32_bf16 v[30:33], v[222:225], v[180:183], v[30:33]
	v_mfma_f32_16x16x32_bf16 v[22:25], v[214:217], v[188:191], v[22:25]
	v_mfma_f32_16x16x32_bf16 v[14:17], v[222:225], v[188:191], v[14:17]
	v_mfma_f32_16x16x32_bf16 v[6:9], v[214:217], v[196:199], v[6:9]
	v_mfma_f32_16x16x32_bf16 v[2:5], v[222:225], v[196:199], v[2:5]
	v_mfma_f32_16x16x32_bf16 v[54:57], v[218:221], v[176:179], v[54:57]
	v_mfma_f32_16x16x32_bf16 v[46:49], v[226:229], v[176:179], v[46:49]
	v_mfma_f32_16x16x32_bf16 v[38:41], v[218:221], v[184:187], v[38:41]
	v_mfma_f32_16x16x32_bf16 v[30:33], v[226:229], v[184:187], v[30:33]
	v_mfma_f32_16x16x32_bf16 v[22:25], v[218:221], v[192:195], v[22:25]
	v_mfma_f32_16x16x32_bf16 v[14:17], v[226:229], v[192:195], v[14:17]
	v_mfma_f32_16x16x32_bf16 v[6:9], v[218:221], v[200:203], v[6:9]
	s_barrier
	v_mfma_f32_16x16x32_bf16 v[2:5], v[226:229], v[200:203], v[2:5]
	s_setprio 0
	s_add_i32 s44, 0, 0x18000
	v_add_u32_e32 v168, s44, v151
	ds_read_b128 v[156:159], v168
	ds_read_b128 v[160:163], v168 offset:1024
	ds_read_b128 v[164:167], v168 offset:2048
	ds_read_b128 v[168:171], v168 offset:3072
	s_add_u32 s26, s26, 0x80000
	s_addc_u32 s27, s27, 0
	s_mov_b32 m0, s31
	v_lshl_add_u64 v[214:215], s[26:27], 0, v[130:131]
	ds_read_b128 v[172:175], v154 offset:32768
	ds_read_b128 v[176:179], v154 offset:33792
	ds_read_b128 v[180:183], v154 offset:34816
	ds_read_b128 v[184:187], v154 offset:35840
	ds_read_b128 v[188:191], v154 offset:36864
	ds_read_b128 v[192:195], v154 offset:37888
	ds_read_b128 v[196:199], v154 offset:38912
	ds_read_b128 v[200:203], v154 offset:39936
	global_load_lds_dwordx4 v[214:215], off
	v_lshl_add_u64 v[214:215], s[26:27], 0, v[132:133]
	s_mov_b32 m0, s33
	s_nop 0
	global_load_lds_dwordx4 v[214:215], off
	s_waitcnt lgkmcnt(8)
	s_barrier
	s_waitcnt lgkmcnt(0)
	s_setprio 1
	s_waitcnt lgkmcnt(0)
	v_mfma_f32_16x16x32_bf16 v[126:129], v[156:159], v[172:175], v[126:129]
	v_mfma_f32_16x16x32_bf16 v[122:125], v[164:167], v[172:175], v[122:125]
	v_mfma_f32_16x16x32_bf16 v[110:113], v[156:159], v[180:183], v[110:113]
	v_mfma_f32_16x16x32_bf16 v[106:109], v[164:167], v[180:183], v[106:109]
	v_mfma_f32_16x16x32_bf16 v[98:101], v[156:159], v[188:191], v[98:101]
	v_mfma_f32_16x16x32_bf16 v[90:93], v[164:167], v[188:191], v[90:93]
	v_mfma_f32_16x16x32_bf16 v[82:85], v[156:159], v[196:199], v[82:85]
	v_mfma_f32_16x16x32_bf16 v[74:77], v[164:167], v[196:199], v[74:77]
	v_mfma_f32_16x16x32_bf16 v[126:129], v[160:163], v[176:179], v[126:129]
	v_mfma_f32_16x16x32_bf16 v[122:125], v[168:171], v[176:179], v[122:125]
	v_mfma_f32_16x16x32_bf16 v[110:113], v[160:163], v[184:187], v[110:113]
	v_mfma_f32_16x16x32_bf16 v[106:109], v[168:171], v[184:187], v[106:109]
	v_mfma_f32_16x16x32_bf16 v[98:101], v[160:163], v[192:195], v[98:101]
	v_mfma_f32_16x16x32_bf16 v[90:93], v[168:171], v[192:195], v[90:93]
	v_mfma_f32_16x16x32_bf16 v[82:85], v[160:163], v[200:203], v[82:85]
	s_barrier
	v_mfma_f32_16x16x32_bf16 v[74:77], v[168:171], v[200:203], v[74:77]
	s_setprio 0
	s_add_i32 s26, 0, 0x1c000
	s_add_i32 s27, s44, s24
	v_add_u32_e32 v204, s26, v151
	v_lshl_add_u64 v[142:143], v[142:143], 0, s[6:7]
	s_mov_b32 m0, s27
	ds_read_b128 v[214:217], v204
	ds_read_b128 v[218:221], v204 offset:1024
	ds_read_b128 v[222:225], v204 offset:2048
	ds_read_b128 v[226:229], v204 offset:3072
	global_load_lds_dwordx4 v[142:143], off
	v_lshl_add_u64 v[142:143], v[206:207], 0, s[6:7]
	s_add_i32 m0, s27, 0x2000
	s_nop 0
	global_load_lds_dwordx4 v[142:143], off
	s_barrier
	s_waitcnt lgkmcnt(0)
	s_setprio 1
	s_waitcnt lgkmcnt(0)
	v_mfma_f32_16x16x32_bf16 v[118:121], v[214:217], v[172:175], v[118:121]
	v_mfma_f32_16x16x32_bf16 v[114:117], v[222:225], v[172:175], v[114:117]
	v_mfma_f32_16x16x32_bf16 v[102:105], v[214:217], v[180:183], v[102:105]
	v_mfma_f32_16x16x32_bf16 v[94:97], v[222:225], v[180:183], v[94:97]
	v_mfma_f32_16x16x32_bf16 v[86:89], v[214:217], v[188:191], v[86:89]
	v_mfma_f32_16x16x32_bf16 v[78:81], v[222:225], v[188:191], v[78:81]
	v_mfma_f32_16x16x32_bf16 v[70:73], v[214:217], v[196:199], v[70:73]
	v_mfma_f32_16x16x32_bf16 v[66:69], v[222:225], v[196:199], v[66:69]
	v_mfma_f32_16x16x32_bf16 v[118:121], v[218:221], v[176:179], v[118:121]
	v_mfma_f32_16x16x32_bf16 v[114:117], v[226:229], v[176:179], v[114:117]
	v_mfma_f32_16x16x32_bf16 v[102:105], v[218:221], v[184:187], v[102:105]
	v_mfma_f32_16x16x32_bf16 v[94:97], v[226:229], v[184:187], v[94:97]
	v_mfma_f32_16x16x32_bf16 v[86:89], v[218:221], v[192:195], v[86:89]
	v_mfma_f32_16x16x32_bf16 v[78:81], v[226:229], v[192:195], v[78:81]
	v_mfma_f32_16x16x32_bf16 v[70:73], v[218:221], v[200:203], v[70:73]
	s_barrier
	v_mfma_f32_16x16x32_bf16 v[66:69], v[226:229], v[200:203], v[66:69]
	s_setprio 0
	s_mov_b32 m0, s36
	v_lshl_add_u64 v[142:143], v[230:231], 0, s[6:7]
	ds_read_b128 v[172:175], v154 offset:49152
	ds_read_b128 v[176:179], v154 offset:50176
	ds_read_b128 v[180:183], v154 offset:51200
	ds_read_b128 v[184:187], v154 offset:52224
	ds_read_b128 v[188:191], v154 offset:53248
	ds_read_b128 v[192:195], v154 offset:54272
	ds_read_b128 v[196:199], v154 offset:55296
	ds_read_b128 v[200:203], v154 offset:56320
	global_load_lds_dwordx4 v[142:143], off
	v_lshl_add_u64 v[142:143], v[232:233], 0, s[6:7]
	s_mov_b32 m0, s37
	s_nop 0
	global_load_lds_dwordx4 v[142:143], off
	s_barrier
; #define PG8_STAGE(bufoff, gbase, voff) do { _Pragma("unroll") for (int _i = 0; _i < 2; ++_i) \
;         __builtin_amdgcn_global_load_lds((const unsigned*)((const char*)(gbase) + (voff)[_i]), (LAS unsigned*)(lds + (bufoff) + ldsw + _i * 8192), 16, 0, 0); } while (0)
; #define PG8_LDA(dst, b, h) do { _Pragma("unroll") for (int m = 0; m < 4; ++m) _Pragma("unroll") for (int k = 0; k < 2; ++k) dst[m][k] = *(const LAS bf16x8*)(lds + PG8_SA(b, h) + aoff + m * 2048 + k * 1024); } while (0)
; #define PG8_LDB(dst, b, h) do { _Pragma("unroll") for (int n = 0; n < 2; ++n) _Pragma("unroll") for (int k = 0; k < 2; ++k) dst[n][k] = *(const LAS bf16x8*)(lds + PG8_SB(b, h) + boff + n * 2048 + k * 1024); } while (0)
; #define PG8_WAIT_V(n) asm volatile("s_waitcnt vmcnt(" #n ")" ::: "memory")
; #define PG8_WAIT_L(n) asm volatile("s_waitcnt lgkmcnt(" #n ")" ::: "memory")
; #define PG8_BAR __builtin_amdgcn_s_barrier()
; #define PG8_SCHED __builtin_amdgcn_sched_barrier(0)
; template <class Epi, class Sched>
; __device__ __forceinline__ void gemm_phase(LAS unsigned char* lds, const Gemm g, const Sched S, const Epi E) {
;     ...
;             PG8_LDB(B0, 1, 0); PG8_SCHED; PG8_LDA(At, 1, 0); PG8_STAGE(PG8_SA(0, 1), a2 + hstep, voffA);
;             PG8_WAIT_L(8); PG8_BAR; PG8_WAIT_L(0); PG8_MMA(0, 0, At, B0); PG8_BAR; PG8_SCHED;
;             PG8_LDB(B1, 1, 1); PG8_STAGE(PG8_SB(1, 0), b3, voffB);
;             PG8_BAR; PG8_WAIT_L(0); PG8_MMA(0, 1, At, B1); PG8_BAR;
;             PG8_LDA(At, 1, 1); PG8_STAGE(PG8_SA(1, 0), a3, voffA);
;             PG8_BAR; PG8_WAIT_L(0); PG8_MMA(1, 0, At, B0); PG8_BAR; PG8_SCHED;
;             PG8_STAGE(PG8_SB(1, 1), b3 + hstep, voffB);
;             PG8_WAIT_V(6); PG8_BAR; PG8_MMA(1, 1, At, B1); PG8_BAR;
;     __device__ __forceinline__ void operator()(const f32x4 (&acc)[2][2][4][2], const Unit& u, int wr, int wc, int fr, int fq) const {
;         const int row0 = u.pm * 256 + wr * 64 + fr, col0 = u.pn * 256 + wc * 32 + 4 * fq;
; #pragma unroll
;         for (int ai = 0; ai < 2; ++ai) {
;             u32x2 bv[4][2][2];
; #pragma unroll
;             for (int m = 0; m < 4; ++m) { const int off = (row0 + ai * HALF + m * 16) * DM + col0;
; #pragma unroll
;                 for (int bj = 0; bj < 2; ++bj)
; #pragma unroll
;                     for (int n = 0; n < 2; ++n) bv[m][bj][n] = *(const u32x2*)(base + off + bj * HALF + n * 16); }
	s_waitcnt lgkmcnt(0)
	s_setprio 1
	s_waitcnt lgkmcnt(0)
	v_mfma_f32_16x16x32_bf16 v[62:65], v[156:159], v[172:175], v[62:65]
	v_mfma_f32_16x16x32_bf16 v[58:61], v[164:167], v[172:175], v[58:61]
	v_mfma_f32_16x16x32_bf16 v[50:53], v[156:159], v[180:183], v[50:53]
	v_mfma_f32_16x16x32_bf16 v[42:45], v[164:167], v[180:183], v[42:45]
	v_mfma_f32_16x16x32_bf16 v[34:37], v[156:159], v[188:191], v[34:37]
	v_mfma_f32_16x16x32_bf16 v[26:29], v[164:167], v[188:191], v[26:29]
	v_mfma_f32_16x16x32_bf16 v[18:21], v[156:159], v[196:199], v[18:21]
	v_mfma_f32_16x16x32_bf16 v[10:13], v[164:167], v[196:199], v[10:13]
	v_mfma_f32_16x16x32_bf16 v[62:65], v[160:163], v[176:179], v[62:65]
	v_mfma_f32_16x16x32_bf16 v[58:61], v[168:171], v[176:179], v[58:61]
	v_mfma_f32_16x16x32_bf16 v[50:53], v[160:163], v[184:187], v[50:53]
	v_mfma_f32_16x16x32_bf16 v[42:45], v[168:171], v[184:187], v[42:45]
	v_mfma_f32_16x16x32_bf16 v[34:37], v[160:163], v[192:195], v[34:37]
	v_mfma_f32_16x16x32_bf16 v[26:29], v[168:171], v[192:195], v[26:29]
	v_mfma_f32_16x16x32_bf16 v[18:21], v[160:163], v[200:203], v[18:21]
	s_barrier
	v_mfma_f32_16x16x32_bf16 v[10:13], v[168:171], v[200:203], v[10:13]
	s_setprio 0
	s_add_u32 s22, s22, 0x80080
	s_addc_u32 s23, s23, 0
	s_add_i32 s26, s26, s24
	v_lshl_add_u64 v[142:143], s[22:23], 0, v[130:131]
	s_mov_b32 m0, s26
	s_nop 0
	global_load_lds_dwordx4 v[142:143], off
	v_lshl_add_u64 v[142:143], s[22:23], 0, v[132:133]
	s_add_i32 m0, s26, 0x2000
	s_nop 0
	global_load_lds_dwordx4 v[142:143], off
	s_waitcnt vmcnt(6)
	s_barrier
	s_setprio 1
	v_mfma_f32_16x16x32_bf16 v[54:57], v[214:217], v[172:175], v[54:57]
	v_mfma_f32_16x16x32_bf16 v[46:49], v[222:225], v[172:175], v[46:49]
	v_mfma_f32_16x16x32_bf16 v[38:41], v[214:217], v[180:183], v[38:41]
	v_mfma_f32_16x16x32_bf16 v[30:33], v[222:225], v[180:183], v[30:33]
	v_mfma_f32_16x16x32_bf16 v[22:25], v[214:217], v[188:191], v[22:25]
	v_mfma_f32_16x16x32_bf16 v[14:17], v[222:225], v[188:191], v[14:17]
	v_mfma_f32_16x16x32_bf16 v[6:9], v[214:217], v[196:199], v[6:9]
	v_mfma_f32_16x16x32_bf16 v[2:5], v[222:225], v[196:199], v[2:5]
	v_mfma_f32_16x16x32_bf16 v[54:57], v[218:221], v[176:179], v[54:57]
	v_mfma_f32_16x16x32_bf16 v[46:49], v[226:229], v[176:179], v[46:49]
	v_mfma_f32_16x16x32_bf16 v[38:41], v[218:221], v[184:187], v[38:41]
	v_mfma_f32_16x16x32_bf16 v[30:33], v[226:229], v[184:187], v[30:33]
	v_mfma_f32_16x16x32_bf16 v[22:25], v[218:221], v[192:195], v[22:25]
	v_mfma_f32_16x16x32_bf16 v[14:17], v[226:229], v[192:195], v[14:17]
	v_mfma_f32_16x16x32_bf16 v[6:9], v[218:221], v[200:203], v[6:9]
	s_barrier
	v_mfma_f32_16x16x32_bf16 v[2:5], v[226:229], v[200:203], v[2:5]
	s_setprio 0
	s_add_i32 s43, s43, 2
	s_add_u32 s20, s20, 0x100
	s_addc_u32 s21, s21, 0
	s_add_u32 s41, s41, 0x100
	s_addc_u32 s42, s42, 0
	s_cmp_gt_u32 s43, 29
	s_cbranch_scc0 .LBB0_1330
	s_lshl_b32 s2, s2, 8
	s_lshl_b32 s9, s18, 19
	s_add_i32 s9, s9, s2
	v_add_u32_e32 v142, s9, v152
	v_ashrrev_i32_e32 v143, 31, v142
	v_add_u32_e32 v166, 0x8000, v142
	v_lshl_add_u64 v[156:157], v[142:143], 1, s[74:75]
	v_ashrrev_i32_e32 v167, 31, v166
	global_load_dwordx2 v[158:159], v[156:157], off
	global_load_dwordx2 v[160:161], v[156:157], off offset:32
	global_load_dwordx2 v[162:163], v[156:157], off offset:256
	global_load_dwordx2 v[164:165], v[156:157], off offset:288
	v_lshl_add_u64 v[166:167], v[166:167], 1, s[74:75]
	global_load_dwordx2 v[168:169], v[166:167], off
	global_load_dwordx2 v[170:171], v[166:167], off offset:32
	global_load_dwordx2 v[176:177], v[166:167], off offset:256
	v_add_u32_e32 v172, 0x10000, v142
	v_add_u32_e32 v174, 0x18000, v142
	v_ashrrev_i32_e32 v173, 31, v172
	v_ashrrev_i32_e32 v175, 31, v174
	v_lshl_add_u64 v[172:173], v[172:173], 1, s[74:75]
	v_lshl_add_u64 v[174:175], v[174:175], 1, s[74:75]
	global_load_dwordx2 v[178:179], v[166:167], off offset:288
	global_load_dwordx2 v[180:181], v[172:173], off
	global_load_dwordx2 v[182:183], v[172:173], off offset:32
	global_load_dwordx2 v[184:185], v[172:173], off offset:256
	global_load_dwordx2 v[186:187], v[172:173], off offset:288
	global_load_dwordx2 v[188:189], v[174:175], off
	global_load_dwordx2 v[190:191], v[174:175], off offset:32
	global_load_dwordx2 v[192:193], v[174:175], off offset:256
	global_load_dwordx2 v[194:195], v[174:175], off offset:288
	s_and_b64 vcc, exec, s[4:5]
	s_mov_b32 s2, s8
	s_mov_b32 s18, s10
	s_mov_b64 s[22:23], s[16:17]
	s_mov_b64 s[20:21], s[12:13]
	v_add_u32_e32 v248, 0x40000, v142
	v_ashrrev_i32_e32 v249, 31, v248
	v_lshl_add_u64 v[248:249], v[248:249], 1, s[74:75]
	v_add_u32_e32 v250, 0x48000, v142
	v_ashrrev_i32_e32 v251, 31, v250
	v_lshl_add_u64 v[250:251], v[250:251], 1, s[74:75]
	v_add_u32_e32 v252, 0x50000, v142
	v_ashrrev_i32_e32 v253, 31, v252
	v_lshl_add_u64 v[252:253], v[252:253], 1, s[74:75]
	v_add_u32_e32 v254, 0x58000, v142
	v_ashrrev_i32_e32 v255, 31, v254
	v_lshl_add_u64 v[254:255], v[254:255], 1, s[74:75]
	global_load_dwordx2 v[214:215], v[248:249], off
	global_load_dwordx2 v[216:217], v[248:249], off offset:32
	global_load_dwordx2 v[218:219], v[248:249], off offset:256
	global_load_dwordx2 v[220:221], v[248:249], off offset:288
	global_load_dwordx2 v[222:223], v[250:251], off
	global_load_dwordx2 v[224:225], v[250:251], off offset:32
	global_load_dwordx2 v[226:227], v[250:251], off offset:256
	global_load_dwordx2 v[228:229], v[250:251], off offset:288
	global_load_dwordx2 v[230:231], v[252:253], off
	global_load_dwordx2 v[232:233], v[252:253], off offset:32
	global_load_dwordx2 v[234:235], v[252:253], off offset:256
	global_load_dwordx2 v[236:237], v[252:253], off offset:288
	global_load_dwordx2 v[238:239], v[254:255], off
	global_load_dwordx2 v[240:241], v[254:255], off offset:32
	global_load_dwordx2 v[242:243], v[254:255], off offset:256
	global_load_dwordx2 v[246:247], v[254:255], off offset:288
	s_waitcnt vmcnt(16)
; __device__ __forceinline__ unsigned cvtpk(float lo, float hi) { unsigned r; asm volatile("v_cvt_pk_bf16_f32 %0, %1, %2" : "=v"(r) : "v"(lo), "v"(hi)); return r; }
;     __device__ __forceinline__ void operator()(const f32x4 (&acc)[2][2][4][2], const Unit& u, int wr, int wc, int fr, int fq) const {
;     ...
;             for (int m = 0; m < 4; ++m) { const int off = (row0 + ai * HALF + m * 16) * DM + col0;
; #pragma unroll
;                 for (int bj = 0; bj < 2; ++bj)
; #pragma unroll
;                     for (int n = 0; n < 2; ++n) { const u32x2 b = bv[m][bj][n]; const f32x4 a4 = acc[ai][bj][m][n];
;                         const float v0 = __uint_as_float(b.x << 16) + a4[0] * s, v1 = __uint_as_float(b.x & 0xffff0000u) + a4[1] * s, v2 = __uint_as_float(b.y << 16) + a4[2] * s, v3 = __uint_as_float(b.y & 0xffff0000u) + a4[3] * s;
;                         u32x2 w; w.x = cvtpk(v0, v1); w.y = cvtpk(v2, v3); *(u32x2*)(xb + off + bj * HALF + n * 16) = w; } }
	v_lshlrev_b32_e32 v143, 16, v158
	v_and_b32_e32 v158, 0xffff0000, v158
	v_lshlrev_b32_e32 v200, 16, v163
	v_and_b32_e32 v163, 0xffff0000, v163
	v_lshlrev_b32_e32 v201, 16, v164
	v_and_b32_e32 v164, 0xffff0000, v164
	v_lshlrev_b32_e32 v196, 16, v159
	v_and_b32_e32 v159, 0xffff0000, v159
	v_lshlrev_b32_e32 v197, 16, v160
	v_and_b32_e32 v160, 0xffff0000, v160
	v_lshlrev_b32_e32 v198, 16, v161
	v_and_b32_e32 v161, 0xffff0000, v161
	v_add_f32_e32 v126, v126, v143
	v_add_f32_e32 v127, v127, v158
	v_add_f32_e32 v121, v121, v163
	v_add_f32_e32 v158, v115, v164
	v_lshlrev_b32_e32 v163, 16, v170
	v_and_b32_e32 v164, 0xffff0000, v170
	v_lshlrev_b32_e32 v199, 16, v162
	v_and_b32_e32 v162, 0xffff0000, v162
	v_add_f32_e32 v128, v128, v196
	v_add_f32_e32 v129, v129, v159
	v_add_f32_e32 v122, v122, v197
	v_add_f32_e32 v123, v123, v160
	v_add_f32_e32 v124, v124, v198
	v_add_f32_e32 v125, v125, v161
	v_add_f32_e32 v143, v114, v201
	v_cvt_pk_bf16_f32 v114, v126, v127
	v_cvt_pk_bf16_f32 v115, v128, v129
	v_add_f32_e32 v126, v106, v163
	v_add_f32_e32 v127, v107, v164
	global_store_dwordx2 v[156:157], v[114:115], off
	v_cvt_pk_bf16_f32 v106, v122, v123
	v_cvt_pk_bf16_f32 v107, v124, v125
	v_lshlrev_b32_e32 v202, 16, v165
	v_and_b32_e32 v165, 0xffff0000, v165
	v_add_f32_e32 v118, v118, v199
	v_add_f32_e32 v119, v119, v162
	v_add_f32_e32 v120, v120, v200
	global_store_dwordx2 v[156:157], v[106:107], off offset:32
	v_cvt_pk_bf16_f32 v106, v118, v119
	v_cvt_pk_bf16_f32 v107, v120, v121
	v_add_f32_e32 v116, v116, v202
	v_add_f32_e32 v117, v117, v165
	v_lshlrev_b32_e32 v159, 16, v168
	v_and_b32_e32 v160, 0xffff0000, v168
	v_lshlrev_b32_e32 v161, 16, v169
	v_and_b32_e32 v162, 0xffff0000, v169
	global_store_dwordx2 v[156:157], v[106:107], off offset:256
	v_cvt_pk_bf16_f32 v106, v143, v158
	v_cvt_pk_bf16_f32 v107, v116, v117
	v_and_b32_e32 v168, 0xffff0000, v171
	v_add_f32_e32 v110, v110, v159
	v_add_f32_e32 v111, v111, v160
	v_add_f32_e32 v112, v112, v161
	v_add_f32_e32 v113, v113, v162
	global_store_dwordx2 v[156:157], v[106:107], off offset:288
	v_cvt_pk_bf16_f32 v106, v110, v111
	v_cvt_pk_bf16_f32 v107, v112, v113
	v_lshlrev_b32_e32 v165, 16, v171
	global_store_dwordx2 v[166:167], v[106:107], off
	v_add_f32_e32 v107, v109, v168
	v_cvt_pk_bf16_f32 v106, v126, v127
	v_add_f32_e32 v108, v108, v165
	v_cvt_pk_bf16_f32 v107, v108, v107
	global_store_dwordx2 v[166:167], v[106:107], off offset:32
	v_lshlrev_b32_e32 v106, 16, v176
	v_add_f32_e32 v102, v102, v106
	v_and_b32_e32 v106, 0xffff0000, v176
	v_add_f32_e32 v103, v103, v106
	v_lshlrev_b32_e32 v106, 16, v177
	v_add_f32_e32 v104, v104, v106
	v_and_b32_e32 v106, 0xffff0000, v177
	v_cvt_pk_bf16_f32 v102, v102, v103
	v_add_f32_e32 v105, v105, v106
	v_cvt_pk_bf16_f32 v103, v104, v105
	global_store_dwordx2 v[166:167], v[102:103], off offset:256
	v_lshlrev_b32_e32 v102, 16, v178
	v_add_f32_e32 v94, v94, v102
	v_and_b32_e32 v102, 0xffff0000, v178
	v_add_f32_e32 v95, v95, v102
	v_lshlrev_b32_e32 v102, 16, v179
	v_add_f32_e32 v96, v96, v102
	v_and_b32_e32 v102, 0xffff0000, v179
	v_cvt_pk_bf16_f32 v94, v94, v95
	v_add_f32_e32 v97, v97, v102
	v_cvt_pk_bf16_f32 v95, v96, v97
	global_store_dwordx2 v[166:167], v[94:95], off offset:288
	v_lshlrev_b32_e32 v94, 16, v180
	v_add_f32_e32 v94, v98, v94
	v_and_b32_e32 v95, 0xffff0000, v180
	v_add_f32_e32 v95, v99, v95
	v_lshlrev_b32_e32 v96, 16, v181
	v_and_b32_e32 v97, 0xffff0000, v181
	v_cvt_pk_bf16_f32 v94, v94, v95
	v_add_f32_e32 v96, v100, v96
	v_add_f32_e32 v97, v101, v97
	v_cvt_pk_bf16_f32 v95, v96, v97
	global_store_dwordx2 v[172:173], v[94:95], off
	v_lshlrev_b32_e32 v94, 16, v182
	v_add_f32_e32 v90, v90, v94
	v_and_b32_e32 v94, 0xffff0000, v182
	v_add_f32_e32 v91, v91, v94
	v_lshlrev_b32_e32 v94, 16, v183
	v_add_f32_e32 v92, v92, v94
	v_and_b32_e32 v94, 0xffff0000, v183
	v_cvt_pk_bf16_f32 v90, v90, v91
	v_add_f32_e32 v93, v93, v94
	v_cvt_pk_bf16_f32 v91, v92, v93
	global_store_dwordx2 v[172:173], v[90:91], off offset:32
	v_lshlrev_b32_e32 v90, 16, v184
	v_add_f32_e32 v86, v86, v90
	v_and_b32_e32 v90, 0xffff0000, v184
	v_add_f32_e32 v87, v87, v90
	v_lshlrev_b32_e32 v90, 16, v185
	v_add_f32_e32 v88, v88, v90
	v_and_b32_e32 v90, 0xffff0000, v185
	v_cvt_pk_bf16_f32 v86, v86, v87
	v_add_f32_e32 v89, v89, v90
	v_cvt_pk_bf16_f32 v87, v88, v89
	global_store_dwordx2 v[172:173], v[86:87], off offset:256
	v_lshlrev_b32_e32 v86, 16, v186
	v_add_f32_e32 v78, v78, v86
	v_and_b32_e32 v86, 0xffff0000, v186
	v_add_f32_e32 v79, v79, v86
	v_lshlrev_b32_e32 v86, 16, v187
	v_add_f32_e32 v80, v80, v86
	v_and_b32_e32 v86, 0xffff0000, v187
	v_cvt_pk_bf16_f32 v78, v78, v79
	v_add_f32_e32 v81, v81, v86
	v_cvt_pk_bf16_f32 v79, v80, v81
	global_store_dwordx2 v[172:173], v[78:79], off offset:288
	v_lshlrev_b32_e32 v78, 16, v188
	v_add_f32_e32 v78, v82, v78
	v_and_b32_e32 v79, 0xffff0000, v188
	v_add_f32_e32 v79, v83, v79
	v_lshlrev_b32_e32 v80, 16, v189
	v_and_b32_e32 v81, 0xffff0000, v189
	v_cvt_pk_bf16_f32 v78, v78, v79
	v_add_f32_e32 v80, v84, v80
	v_add_f32_e32 v81, v85, v81
	v_cvt_pk_bf16_f32 v79, v80, v81
	global_store_dwordx2 v[174:175], v[78:79], off
	v_lshlrev_b32_e32 v78, 16, v190
	v_add_f32_e32 v74, v74, v78
	v_and_b32_e32 v78, 0xffff0000, v190
	v_add_f32_e32 v75, v75, v78
	v_lshlrev_b32_e32 v78, 16, v191
	v_add_f32_e32 v76, v76, v78
	v_and_b32_e32 v78, 0xffff0000, v191
	v_cvt_pk_bf16_f32 v74, v74, v75
	v_add_f32_e32 v77, v77, v78
	v_cvt_pk_bf16_f32 v75, v76, v77
	global_store_dwordx2 v[174:175], v[74:75], off offset:32
	v_lshlrev_b32_e32 v74, 16, v192
	v_add_f32_e32 v70, v70, v74
	v_and_b32_e32 v74, 0xffff0000, v192
	v_add_f32_e32 v71, v71, v74
	v_lshlrev_b32_e32 v74, 16, v193
	v_add_f32_e32 v72, v72, v74
	v_and_b32_e32 v74, 0xffff0000, v193
	v_cvt_pk_bf16_f32 v70, v70, v71
	v_add_f32_e32 v73, v73, v74
	v_cvt_pk_bf16_f32 v71, v72, v73
	global_store_dwordx2 v[174:175], v[70:71], off offset:256
	v_lshlrev_b32_e32 v70, 16, v194
	v_add_f32_e32 v66, v66, v70
	v_and_b32_e32 v70, 0xffff0000, v194
	v_add_f32_e32 v67, v67, v70
	v_lshlrev_b32_e32 v70, 16, v195
	v_add_f32_e32 v68, v68, v70
	v_and_b32_e32 v70, 0xffff0000, v195
	v_cvt_pk_bf16_f32 v66, v66, v67
	v_add_f32_e32 v69, v69, v70
	v_cvt_pk_bf16_f32 v67, v68, v69
	global_store_dwordx2 v[174:175], v[66:67], off offset:288
	v_add_u32_e32 v66, 0x40000, v142
	v_ashrrev_i32_e32 v67, 31, v66
	v_lshl_add_u64 v[66:67], v[66:67], 1, s[74:75]
	v_add_u32_e32 v76, 0x48000, v142
	v_ashrrev_i32_e32 v77, 31, v76
	v_lshl_add_u64 v[76:77], v[76:77], 1, s[74:75]
	v_add_u32_e32 v86, 0x50000, v142
	v_ashrrev_i32_e32 v87, 31, v86
	v_lshl_add_u64 v[86:87], v[86:87], 1, s[74:75]
	v_add_u32_e32 v96, 0x58000, v142
	v_ashrrev_i32_e32 v97, 31, v96
	v_lshl_add_u64 v[96:97], v[96:97], 1, s[74:75]
	s_waitcnt vmcnt(16)
; __device__ __forceinline__ unsigned cvtpk(float lo, float hi) { unsigned r; asm volatile("v_cvt_pk_bf16_f32 %0, %1, %2" : "=v"(r) : "v"(lo), "v"(hi)); return r; }
;     __device__ __forceinline__ void operator()(const f32x4 (&acc)[2][2][4][2], const Unit& u, int wr, int wc, int fr, int fq) const {
;     ...
;             for (int m = 0; m < 4; ++m) { const int off = (row0 + ai * HALF + m * 16) * DM + col0;
; #pragma unroll
;                 for (int bj = 0; bj < 2; ++bj)
; #pragma unroll
;                     for (int n = 0; n < 2; ++n) { const u32x2 b = bv[m][bj][n]; const f32x4 a4 = acc[ai][bj][m][n];
;                         const float v0 = __uint_as_float(b.x << 16) + a4[0] * s, v1 = __uint_as_float(b.x & 0xffff0000u) + a4[1] * s, v2 = __uint_as_float(b.y << 16) + a4[2] * s, v3 = __uint_as_float(b.y & 0xffff0000u) + a4[3] * s;
;                         u32x2 w; w.x = cvtpk(v0, v1); w.y = cvtpk(v2, v3); *(u32x2*)(xb + off + bj * HALF + n * 16) = w; } }
	v_lshlrev_b32_e32 v106, 16, v214
	v_and_b32_e32 v68, 0xffff0000, v214
	v_add_f32_e32 v62, v62, v106
	v_add_f32_e32 v63, v63, v68
	v_lshlrev_b32_e32 v68, 16, v215
	v_add_f32_e32 v64, v64, v68
	v_and_b32_e32 v68, 0xffff0000, v215
	v_cvt_pk_bf16_f32 v62, v62, v63
	v_add_f32_e32 v65, v65, v68
	v_cvt_pk_bf16_f32 v63, v64, v65
	global_store_dwordx2 v[66:67], v[62:63], off
	v_lshlrev_b32_e32 v62, 16, v216
	v_add_f32_e32 v58, v58, v62
	v_and_b32_e32 v62, 0xffff0000, v216
	v_add_f32_e32 v59, v59, v62
	v_lshlrev_b32_e32 v62, 16, v217
	v_add_f32_e32 v60, v60, v62
	v_and_b32_e32 v62, 0xffff0000, v217
	v_cvt_pk_bf16_f32 v58, v58, v59
	v_add_f32_e32 v61, v61, v62
	v_cvt_pk_bf16_f32 v59, v60, v61
	global_store_dwordx2 v[66:67], v[58:59], off offset:32
	v_lshlrev_b32_e32 v58, 16, v218
	v_add_f32_e32 v54, v54, v58
	v_and_b32_e32 v58, 0xffff0000, v218
	v_add_f32_e32 v55, v55, v58
	v_lshlrev_b32_e32 v58, 16, v219
	v_add_f32_e32 v56, v56, v58
	v_and_b32_e32 v58, 0xffff0000, v219
	v_cvt_pk_bf16_f32 v54, v54, v55
	v_add_f32_e32 v57, v57, v58
	v_cvt_pk_bf16_f32 v55, v56, v57
	global_store_dwordx2 v[66:67], v[54:55], off offset:256
	v_lshlrev_b32_e32 v54, 16, v220
	v_add_f32_e32 v46, v46, v54
	v_and_b32_e32 v54, 0xffff0000, v220
	v_add_f32_e32 v47, v47, v54
	v_lshlrev_b32_e32 v54, 16, v221
	v_add_f32_e32 v48, v48, v54
	v_and_b32_e32 v54, 0xffff0000, v221
	v_cvt_pk_bf16_f32 v46, v46, v47
	v_add_f32_e32 v49, v49, v54
	v_cvt_pk_bf16_f32 v47, v48, v49
	global_store_dwordx2 v[66:67], v[46:47], off offset:288
	v_lshlrev_b32_e32 v46, 16, v222
	v_add_f32_e32 v46, v50, v46
	v_and_b32_e32 v47, 0xffff0000, v222
	v_add_f32_e32 v47, v51, v47
	v_lshlrev_b32_e32 v48, 16, v223
	v_and_b32_e32 v49, 0xffff0000, v223
	v_cvt_pk_bf16_f32 v46, v46, v47
	v_add_f32_e32 v48, v52, v48
	v_add_f32_e32 v49, v53, v49
	v_cvt_pk_bf16_f32 v47, v48, v49
	global_store_dwordx2 v[76:77], v[46:47], off
	v_lshlrev_b32_e32 v46, 16, v224
	v_add_f32_e32 v42, v42, v46
	v_and_b32_e32 v46, 0xffff0000, v224
	v_add_f32_e32 v43, v43, v46
	v_lshlrev_b32_e32 v46, 16, v225
	v_add_f32_e32 v44, v44, v46
	v_and_b32_e32 v46, 0xffff0000, v225
	v_cvt_pk_bf16_f32 v42, v42, v43
	v_add_f32_e32 v45, v45, v46
	v_cvt_pk_bf16_f32 v43, v44, v45
	global_store_dwordx2 v[76:77], v[42:43], off offset:32
	v_lshlrev_b32_e32 v42, 16, v226
	v_add_f32_e32 v38, v38, v42
	v_and_b32_e32 v42, 0xffff0000, v226
	v_add_f32_e32 v39, v39, v42
	v_lshlrev_b32_e32 v42, 16, v227
	v_add_f32_e32 v40, v40, v42
	v_and_b32_e32 v42, 0xffff0000, v227
	v_cvt_pk_bf16_f32 v38, v38, v39
	v_add_f32_e32 v41, v41, v42
	v_cvt_pk_bf16_f32 v39, v40, v41
	global_store_dwordx2 v[76:77], v[38:39], off offset:256
	v_lshlrev_b32_e32 v38, 16, v228
	v_add_f32_e32 v30, v30, v38
	v_and_b32_e32 v38, 0xffff0000, v228
	v_add_f32_e32 v31, v31, v38
	v_lshlrev_b32_e32 v38, 16, v229
	v_add_f32_e32 v32, v32, v38
	v_and_b32_e32 v38, 0xffff0000, v229
	v_cvt_pk_bf16_f32 v30, v30, v31
	v_add_f32_e32 v33, v33, v38
	v_cvt_pk_bf16_f32 v31, v32, v33
	global_store_dwordx2 v[76:77], v[30:31], off offset:288
	v_lshlrev_b32_e32 v30, 16, v230
	v_add_f32_e32 v30, v34, v30
	v_and_b32_e32 v31, 0xffff0000, v230
	v_add_f32_e32 v31, v35, v31
	v_lshlrev_b32_e32 v32, 16, v231
	v_and_b32_e32 v33, 0xffff0000, v231
	v_cvt_pk_bf16_f32 v30, v30, v31
	v_add_f32_e32 v32, v36, v32
	v_add_f32_e32 v33, v37, v33
	v_cvt_pk_bf16_f32 v31, v32, v33
	global_store_dwordx2 v[86:87], v[30:31], off
	v_lshlrev_b32_e32 v30, 16, v232
	v_add_f32_e32 v26, v26, v30
	v_and_b32_e32 v30, 0xffff0000, v232
	v_add_f32_e32 v27, v27, v30
	v_lshlrev_b32_e32 v30, 16, v233
	v_add_f32_e32 v28, v28, v30
	v_and_b32_e32 v30, 0xffff0000, v233
	v_cvt_pk_bf16_f32 v26, v26, v27
	v_add_f32_e32 v29, v29, v30
	v_cvt_pk_bf16_f32 v27, v28, v29
	global_store_dwordx2 v[86:87], v[26:27], off offset:32
	v_lshlrev_b32_e32 v26, 16, v234
	v_add_f32_e32 v22, v22, v26
	v_and_b32_e32 v26, 0xffff0000, v234
	v_add_f32_e32 v23, v23, v26
	v_lshlrev_b32_e32 v26, 16, v235
	v_add_f32_e32 v24, v24, v26
	v_and_b32_e32 v26, 0xffff0000, v235
	v_cvt_pk_bf16_f32 v22, v22, v23
	v_add_f32_e32 v25, v25, v26
	v_cvt_pk_bf16_f32 v23, v24, v25
	global_store_dwordx2 v[86:87], v[22:23], off offset:256
	v_lshlrev_b32_e32 v22, 16, v236
	v_add_f32_e32 v14, v14, v22
	v_and_b32_e32 v22, 0xffff0000, v236
	v_add_f32_e32 v15, v15, v22
	v_lshlrev_b32_e32 v22, 16, v237
	v_add_f32_e32 v16, v16, v22
	v_and_b32_e32 v22, 0xffff0000, v237
	v_cvt_pk_bf16_f32 v14, v14, v15
	v_add_f32_e32 v17, v17, v22
	v_cvt_pk_bf16_f32 v15, v16, v17
	global_store_dwordx2 v[86:87], v[14:15], off offset:288
	v_lshlrev_b32_e32 v14, 16, v238
	v_add_f32_e32 v14, v18, v14
	v_and_b32_e32 v15, 0xffff0000, v238
	v_add_f32_e32 v15, v19, v15
	v_lshlrev_b32_e32 v16, 16, v239
	v_and_b32_e32 v17, 0xffff0000, v239
	v_cvt_pk_bf16_f32 v14, v14, v15
	v_add_f32_e32 v16, v20, v16
	v_add_f32_e32 v17, v21, v17
	v_cvt_pk_bf16_f32 v15, v16, v17
	global_store_dwordx2 v[96:97], v[14:15], off
	v_lshlrev_b32_e32 v14, 16, v240
	v_add_f32_e32 v10, v10, v14
	v_and_b32_e32 v14, 0xffff0000, v240
	v_add_f32_e32 v11, v11, v14
	v_lshlrev_b32_e32 v14, 16, v241
	v_add_f32_e32 v12, v12, v14
	v_and_b32_e32 v14, 0xffff0000, v241
	v_cvt_pk_bf16_f32 v10, v10, v11
	v_add_f32_e32 v13, v13, v14
	v_cvt_pk_bf16_f32 v11, v12, v13
	global_store_dwordx2 v[96:97], v[10:11], off offset:32
	v_lshlrev_b32_e32 v10, 16, v242
	v_add_f32_e32 v6, v6, v10
	v_and_b32_e32 v10, 0xffff0000, v242
	v_add_f32_e32 v7, v7, v10
	v_lshlrev_b32_e32 v10, 16, v243
	v_add_f32_e32 v8, v8, v10
	v_and_b32_e32 v10, 0xffff0000, v243
	v_cvt_pk_bf16_f32 v6, v6, v7
	v_add_f32_e32 v9, v9, v10
	v_cvt_pk_bf16_f32 v7, v8, v9
	global_store_dwordx2 v[96:97], v[6:7], off offset:256
	v_lshlrev_b32_e32 v6, 16, v246
	v_add_f32_e32 v2, v2, v6
	v_and_b32_e32 v6, 0xffff0000, v246
	v_add_f32_e32 v3, v3, v6
	v_lshlrev_b32_e32 v6, 16, v247
	v_add_f32_e32 v4, v4, v6
	v_and_b32_e32 v6, 0xffff0000, v247
	v_add_f32_e32 v5, v5, v6
	v_cvt_pk_bf16_f32 v2, v2, v3
	v_cvt_pk_bf16_f32 v3, v4, v5
	global_store_dwordx2 v[96:97], v[2:3], off offset:288
	s_cbranch_vccz .LBB0_1323
	s_waitcnt vmcnt(0)
	s_cmpk_gt_u32 s3, 0xff
	s_cbranch_scc1 .LBB0_1334
	s_barrier

; #define PG8_STAGE(bufoff, gbase, voff) do { _Pragma("unroll") for (int _i = 0; _i < 2; ++_i) \
;         __builtin_amdgcn_global_load_lds((const unsigned*)((const char*)(gbase) + (voff)[_i]), (LAS unsigned*)(lds + (bufoff) + ldsw + _i * 8192), 16, 0, 0); } while (0)
; #define PG8_LDA(dst, b, h) do { _Pragma("unroll") for (int m = 0; m < 4; ++m) _Pragma("unroll") for (int k = 0; k < 2; ++k) dst[m][k] = *(const LAS bf16x8*)(lds + PG8_SA(b, h) + aoff + m * 2048 + k * 1024); } while (0)
; #define PG8_WAIT_V(n) asm volatile("s_waitcnt vmcnt(" #n ")" ::: "memory")
; #define PG8_WAIT_L(n) asm volatile("s_waitcnt lgkmcnt(" #n ")" ::: "memory")
; template <class Epi, class Sched>
; __device__ __forceinline__ void gemm_phase(LAS unsigned char* lds, const Gemm g, const Sched S, const Epi E) {
;     ...
;         for (int t = 0; t < nt; t += 2) {
;             const bool last = (t == nt - 2);
;             const char* a1 = cA + (size_t)(t + 1) * kstep;
;             const char* a2 = last ? nA : cA + (size_t)(t + 2) * kstep; const char* b2 = last ? nB : cB + (size_t)(t + 2) * kstep;
;             const char* a3 = a2 + kstep; const char* b3 = b2 + kstep;
;             PG8_LDB(B0, 0, 0); PG8_SCHED; PG8_LDA(At, 0, 0); PG8_STAGE(PG8_SA(1, 1), a1 + hstep, voffA);
;             PG8_WAIT_L(8); PG8_BAR; PG8_WAIT_L(0); PG8_MMA(0, 0, At, B0); PG8_BAR; PG8_SCHED;
;             PG8_LDB(B1, 0, 1); PG8_STAGE(PG8_SB(0, 0), b2, voffB);
;             PG8_BAR; PG8_WAIT_L(0); PG8_MMA(0, 1, At, B1); PG8_BAR;
;             PG8_LDA(At, 0, 1); PG8_STAGE(PG8_SA(0, 0), a2, voffA);
;             PG8_BAR; PG8_WAIT_L(0); PG8_MMA(1, 0, At, B0); PG8_BAR; PG8_SCHED;
;             PG8_STAGE(PG8_SB(0, 1), b2 + hstep, voffB);
;             PG8_WAIT_V(6); PG8_BAR; PG8_MMA(1, 1, At, B1); PG8_BAR;
;             PG8_LDB(B0, 1, 0); PG8_SCHED; PG8_LDA(At, 1, 0); PG8_STAGE(PG8_SA(0, 1), a2 + hstep, voffA);
;             PG8_WAIT_L(8); PG8_BAR; PG8_WAIT_L(0); PG8_MMA(0, 0, At, B0); PG8_BAR; PG8_SCHED;
;             PG8_LDB(B1, 1, 1); PG8_STAGE(PG8_SB(1, 0), b3, voffB);
;             PG8_BAR; PG8_WAIT_L(0); PG8_MMA(0, 1, At, B1); PG8_BAR;
;             PG8_LDA(At, 1, 1); PG8_STAGE(PG8_SA(1, 0), a3, voffA);
;             PG8_BAR; PG8_WAIT_L(0); PG8_MMA(1, 0, At, B0); PG8_BAR; PG8_SCHED;
;             PG8_STAGE(PG8_SB(1, 1), b3 + hstep, voffB);
;             PG8_WAIT_V(6); PG8_BAR; PG8_MMA(1, 1, At, B1); PG8_BAR;
.LBB0_1598:
	ds_read_b128 v[142:145], v156
	ds_read_b128 v[160:163], v156 offset:1024
	ds_read_b128 v[164:167], v156 offset:2048
	ds_read_b128 v[168:171], v156 offset:3072
	s_add_u32 s16, s12, 0xffea0080
	s_addc_u32 s17, s13, -1
	s_cmpk_eq_i32 s37, 0x54
	s_cselect_b32 s19, s7, s17
	s_cselect_b32 s18, s6, s16
	s_cselect_b32 s17, s1, s15
	s_cselect_b32 s16, s0, s14
	v_lshl_add_u64 v[204:205], s[12:13], 0, v[134:135]
	s_add_i32 m0, s22, 0xc000
	ds_read_b128 v[172:175], v157
	ds_read_b128 v[176:179], v157 offset:1024
	ds_read_b128 v[180:183], v157 offset:2048
	ds_read_b128 v[184:187], v157 offset:3072
	ds_read_b128 v[188:191], v157 offset:4096
	ds_read_b128 v[192:195], v157 offset:5120
	ds_read_b128 v[196:199], v157 offset:6144
	ds_read_b128 v[200:203], v157 offset:7168
	global_load_lds_dwordx4 v[204:205], off
	v_lshl_add_u64 v[204:205], s[12:13], 0, v[136:137]
	s_add_i32 m0, s22, 0xe000
	s_nop 0
	global_load_lds_dwordx4 v[204:205], off
	s_waitcnt lgkmcnt(8)
	s_barrier
	s_waitcnt lgkmcnt(0)
	s_setprio 1
	s_waitcnt lgkmcnt(0)
	v_mfma_f32_16x16x32_bf16 v[126:129], v[142:145], v[172:175], v[126:129]
	v_mfma_f32_16x16x32_bf16 v[122:125], v[164:167], v[172:175], v[122:125]
	v_mfma_f32_16x16x32_bf16 v[118:121], v[142:145], v[180:183], v[118:121]
	v_mfma_f32_16x16x32_bf16 v[106:109], v[164:167], v[180:183], v[106:109]
	v_mfma_f32_16x16x32_bf16 v[98:101], v[142:145], v[188:191], v[98:101]
	v_mfma_f32_16x16x32_bf16 v[90:93], v[164:167], v[188:191], v[90:93]
	v_mfma_f32_16x16x32_bf16 v[82:85], v[142:145], v[196:199], v[82:85]
	v_mfma_f32_16x16x32_bf16 v[74:77], v[164:167], v[196:199], v[74:77]
	v_mfma_f32_16x16x32_bf16 v[126:129], v[160:163], v[176:179], v[126:129]
	v_mfma_f32_16x16x32_bf16 v[122:125], v[168:171], v[176:179], v[122:125]
	v_mfma_f32_16x16x32_bf16 v[118:121], v[160:163], v[184:187], v[118:121]
	v_mfma_f32_16x16x32_bf16 v[106:109], v[168:171], v[184:187], v[106:109]
	v_mfma_f32_16x16x32_bf16 v[98:101], v[160:163], v[192:195], v[98:101]
	v_mfma_f32_16x16x32_bf16 v[90:93], v[168:171], v[192:195], v[90:93]
	v_mfma_f32_16x16x32_bf16 v[82:85], v[160:163], v[200:203], v[82:85]
	s_barrier
	v_mfma_f32_16x16x32_bf16 v[74:77], v[168:171], v[200:203], v[74:77]
	s_setprio 0
	s_add_i32 s38, s31, s20
	v_lshl_add_u64 v[210:211], s[16:17], 0, v[130:131]
	s_mov_b32 m0, s38
	ds_read_b128 v[204:207], v158
	ds_read_b128 v[214:217], v158 offset:1024
	ds_read_b128 v[218:221], v158 offset:2048
	ds_read_b128 v[222:225], v158 offset:3072
	global_load_lds_dwordx4 v[210:211], off
	v_lshl_add_u64 v[226:227], s[16:17], 0, v[132:133]
	s_add_i32 m0, s38, 0x2000
	s_nop 0
	global_load_lds_dwordx4 v[226:227], off
	s_barrier
	s_waitcnt lgkmcnt(0)
	s_setprio 1
	s_waitcnt lgkmcnt(0)
	v_mfma_f32_16x16x32_bf16 v[114:117], v[204:207], v[172:175], v[114:117]
	v_mfma_f32_16x16x32_bf16 v[110:113], v[218:221], v[172:175], v[110:113]
	v_mfma_f32_16x16x32_bf16 v[102:105], v[204:207], v[180:183], v[102:105]
	v_mfma_f32_16x16x32_bf16 v[94:97], v[218:221], v[180:183], v[94:97]
	v_mfma_f32_16x16x32_bf16 v[86:89], v[204:207], v[188:191], v[86:89]
	v_mfma_f32_16x16x32_bf16 v[78:81], v[218:221], v[188:191], v[78:81]
	v_mfma_f32_16x16x32_bf16 v[70:73], v[204:207], v[196:199], v[70:73]
	v_mfma_f32_16x16x32_bf16 v[66:69], v[218:221], v[196:199], v[66:69]
	v_mfma_f32_16x16x32_bf16 v[114:117], v[214:217], v[176:179], v[114:117]
	v_mfma_f32_16x16x32_bf16 v[110:113], v[222:225], v[176:179], v[110:113]
	v_mfma_f32_16x16x32_bf16 v[102:105], v[214:217], v[184:187], v[102:105]
	v_mfma_f32_16x16x32_bf16 v[94:97], v[222:225], v[184:187], v[94:97]
	v_mfma_f32_16x16x32_bf16 v[86:89], v[214:217], v[192:195], v[86:89]
	v_mfma_f32_16x16x32_bf16 v[78:81], v[222:225], v[192:195], v[78:81]
	v_mfma_f32_16x16x32_bf16 v[70:73], v[214:217], v[200:203], v[70:73]
	s_barrier
	v_mfma_f32_16x16x32_bf16 v[66:69], v[222:225], v[200:203], v[66:69]
	s_setprio 0
	s_mov_b32 m0, s22
	v_lshl_add_u64 v[228:229], s[18:19], 0, v[130:131]
	ds_read_b128 v[172:175], v157 offset:16384
	ds_read_b128 v[176:179], v157 offset:17408
	ds_read_b128 v[180:183], v157 offset:18432
	ds_read_b128 v[184:187], v157 offset:19456
	ds_read_b128 v[188:191], v157 offset:20480
	ds_read_b128 v[192:195], v157 offset:21504
	ds_read_b128 v[196:199], v157 offset:22528
	ds_read_b128 v[200:203], v157 offset:23552
	global_load_lds_dwordx4 v[228:229], off
	v_lshl_add_u64 v[230:231], s[18:19], 0, v[132:133]
	s_mov_b32 m0, s23
	s_nop 0
	global_load_lds_dwordx4 v[230:231], off
	s_barrier
	s_waitcnt lgkmcnt(0)
	s_setprio 1
	s_waitcnt lgkmcnt(0)
	v_mfma_f32_16x16x32_bf16 v[62:65], v[142:145], v[172:175], v[62:65]
	v_mfma_f32_16x16x32_bf16 v[58:61], v[164:167], v[172:175], v[58:61]
	v_mfma_f32_16x16x32_bf16 v[50:53], v[142:145], v[180:183], v[50:53]
	v_mfma_f32_16x16x32_bf16 v[42:45], v[164:167], v[180:183], v[42:45]
	v_mfma_f32_16x16x32_bf16 v[34:37], v[142:145], v[188:191], v[34:37]
	v_mfma_f32_16x16x32_bf16 v[26:29], v[164:167], v[188:191], v[26:29]
	v_mfma_f32_16x16x32_bf16 v[18:21], v[142:145], v[196:199], v[18:21]
	v_mfma_f32_16x16x32_bf16 v[10:13], v[164:167], v[196:199], v[10:13]
	v_mfma_f32_16x16x32_bf16 v[62:65], v[160:163], v[176:179], v[62:65]
	v_mfma_f32_16x16x32_bf16 v[58:61], v[168:171], v[176:179], v[58:61]
	v_mfma_f32_16x16x32_bf16 v[50:53], v[160:163], v[184:187], v[50:53]
	v_mfma_f32_16x16x32_bf16 v[42:45], v[168:171], v[184:187], v[42:45]
	v_mfma_f32_16x16x32_bf16 v[34:37], v[160:163], v[192:195], v[34:37]
	v_mfma_f32_16x16x32_bf16 v[26:29], v[168:171], v[192:195], v[26:29]
	v_mfma_f32_16x16x32_bf16 v[18:21], v[160:163], v[200:203], v[18:21]
	s_barrier
; #define PG8_STAGE(bufoff, gbase, voff) do { _Pragma("unroll") for (int _i = 0; _i < 2; ++_i) \
;         __builtin_amdgcn_global_load_lds((const unsigned*)((const char*)(gbase) + (voff)[_i]), (LAS unsigned*)(lds + (bufoff) + ldsw + _i * 8192), 16, 0, 0); } while (0)
; #define PG8_LDA(dst, b, h) do { _Pragma("unroll") for (int m = 0; m < 4; ++m) _Pragma("unroll") for (int k = 0; k < 2; ++k) dst[m][k] = *(const LAS bf16x8*)(lds + PG8_SA(b, h) + aoff + m * 2048 + k * 1024); } while (0)
; #define PG8_LDB(dst, b, h) do { _Pragma("unroll") for (int n = 0; n < 2; ++n) _Pragma("unroll") for (int k = 0; k < 2; ++k) dst[n][k] = *(const LAS bf16x8*)(lds + PG8_SB(b, h) + boff + n * 2048 + k * 1024); } while (0)
; #define PG8_WAIT_V(n) asm volatile("s_waitcnt vmcnt(" #n ")" ::: "memory")
; #define PG8_WAIT_L(n) asm volatile("s_waitcnt lgkmcnt(" #n ")" ::: "memory")
; #define PG8_BAR __builtin_amdgcn_s_barrier()
; #define PG8_SCHED __builtin_amdgcn_sched_barrier(0)
; template <class Epi, class Sched>
; __device__ __forceinline__ void gemm_phase(LAS unsigned char* lds, const Gemm g, const Sched S, const Epi E) {
;     ...
;             PG8_LDB(B0, 0, 0); PG8_SCHED; PG8_LDA(At, 0, 0); PG8_STAGE(PG8_SA(1, 1), a1 + hstep, voffA);
;             PG8_WAIT_L(8); PG8_BAR; PG8_WAIT_L(0); PG8_MMA(0, 0, At, B0); PG8_BAR; PG8_SCHED;
;             PG8_LDB(B1, 0, 1); PG8_STAGE(PG8_SB(0, 0), b2, voffB);
;             PG8_BAR; PG8_WAIT_L(0); PG8_MMA(0, 1, At, B1); PG8_BAR;
;             PG8_LDA(At, 0, 1); PG8_STAGE(PG8_SA(0, 0), a2, voffA);
;             PG8_BAR; PG8_WAIT_L(0); PG8_MMA(1, 0, At, B0); PG8_BAR; PG8_SCHED;
;             PG8_STAGE(PG8_SB(0, 1), b2 + hstep, voffB);
;             PG8_WAIT_V(6); PG8_BAR; PG8_MMA(1, 1, At, B1); PG8_BAR;
;             PG8_LDB(B0, 1, 0); PG8_SCHED; PG8_LDA(At, 1, 0); PG8_STAGE(PG8_SA(0, 1), a2 + hstep, voffA);
;             PG8_WAIT_L(8); PG8_BAR; PG8_WAIT_L(0); PG8_MMA(0, 0, At, B0); PG8_BAR; PG8_SCHED;
;             PG8_LDB(B1, 1, 1); PG8_STAGE(PG8_SB(1, 0), b3, voffB);
;             PG8_BAR; PG8_WAIT_L(0); PG8_MMA(0, 1, At, B1); PG8_BAR;
;             PG8_LDA(At, 1, 1); PG8_STAGE(PG8_SA(1, 0), a3, voffA);
;             PG8_BAR; PG8_WAIT_L(0); PG8_MMA(1, 0, At, B0); PG8_BAR; PG8_SCHED;
;             PG8_STAGE(PG8_SB(1, 1), b3 + hstep, voffB);
;             PG8_WAIT_V(6); PG8_BAR; PG8_MMA(1, 1, At, B1); PG8_BAR;
	v_mfma_f32_16x16x32_bf16 v[10:13], v[168:171], v[200:203], v[10:13]
	s_setprio 0
	s_add_u32 s38, s16, 0x160000
	s_addc_u32 s39, s17, 0
	s_add_i32 s40, s33, s20
	v_lshl_add_u64 v[142:143], s[38:39], 0, v[130:131]
	s_mov_b32 m0, s40
	s_nop 0
	global_load_lds_dwordx4 v[142:143], off
	v_lshl_add_u64 v[142:143], s[38:39], 0, v[132:133]
	s_add_i32 m0, s40, 0x2000
	s_nop 0
	global_load_lds_dwordx4 v[142:143], off
	s_waitcnt vmcnt(6)
	s_barrier
	s_setprio 1
	v_mfma_f32_16x16x32_bf16 v[54:57], v[204:207], v[172:175], v[54:57]
	v_mfma_f32_16x16x32_bf16 v[46:49], v[218:221], v[172:175], v[46:49]
	v_mfma_f32_16x16x32_bf16 v[38:41], v[204:207], v[180:183], v[38:41]
	v_mfma_f32_16x16x32_bf16 v[30:33], v[218:221], v[180:183], v[30:33]
	v_mfma_f32_16x16x32_bf16 v[22:25], v[204:207], v[188:191], v[22:25]
	v_mfma_f32_16x16x32_bf16 v[14:17], v[218:221], v[188:191], v[14:17]
	v_mfma_f32_16x16x32_bf16 v[6:9], v[204:207], v[196:199], v[6:9]
	v_mfma_f32_16x16x32_bf16 v[2:5], v[218:221], v[196:199], v[2:5]
	v_mfma_f32_16x16x32_bf16 v[54:57], v[214:217], v[176:179], v[54:57]
	v_mfma_f32_16x16x32_bf16 v[46:49], v[222:225], v[176:179], v[46:49]
	v_mfma_f32_16x16x32_bf16 v[38:41], v[214:217], v[184:187], v[38:41]
	v_mfma_f32_16x16x32_bf16 v[30:33], v[222:225], v[184:187], v[30:33]
	v_mfma_f32_16x16x32_bf16 v[22:25], v[214:217], v[192:195], v[22:25]
	v_mfma_f32_16x16x32_bf16 v[14:17], v[222:225], v[192:195], v[14:17]
	v_mfma_f32_16x16x32_bf16 v[6:9], v[214:217], v[200:203], v[6:9]
	s_barrier
	v_mfma_f32_16x16x32_bf16 v[2:5], v[222:225], v[200:203], v[2:5]
	s_setprio 0
	s_add_i32 s38, 0, 0x18000
	v_add_u32_e32 v159, s38, v154
	ds_read_b128 v[142:145], v159
	ds_read_b128 v[160:163], v159 offset:1024
	ds_read_b128 v[164:167], v159 offset:2048
	ds_read_b128 v[168:171], v159 offset:3072
	s_add_u32 s18, s18, 0x160000
	s_addc_u32 s19, s19, 0
	s_mov_b32 m0, s24
	v_lshl_add_u64 v[204:205], s[18:19], 0, v[130:131]
	ds_read_b128 v[172:175], v157 offset:32768
	ds_read_b128 v[176:179], v157 offset:33792
	ds_read_b128 v[180:183], v157 offset:34816
	ds_read_b128 v[184:187], v157 offset:35840
	ds_read_b128 v[188:191], v157 offset:36864
	ds_read_b128 v[192:195], v157 offset:37888
	ds_read_b128 v[196:199], v157 offset:38912
	ds_read_b128 v[200:203], v157 offset:39936
	global_load_lds_dwordx4 v[204:205], off
	v_lshl_add_u64 v[204:205], s[18:19], 0, v[132:133]
	s_mov_b32 m0, s25
	s_nop 0
	global_load_lds_dwordx4 v[204:205], off
	s_waitcnt lgkmcnt(8)
	s_barrier
	s_waitcnt lgkmcnt(0)
	s_setprio 1
	s_waitcnt lgkmcnt(0)
	v_mfma_f32_16x16x32_bf16 v[126:129], v[142:145], v[172:175], v[126:129]
	v_mfma_f32_16x16x32_bf16 v[122:125], v[164:167], v[172:175], v[122:125]
	v_mfma_f32_16x16x32_bf16 v[118:121], v[142:145], v[180:183], v[118:121]
	v_mfma_f32_16x16x32_bf16 v[106:109], v[164:167], v[180:183], v[106:109]
	v_mfma_f32_16x16x32_bf16 v[98:101], v[142:145], v[188:191], v[98:101]
	v_mfma_f32_16x16x32_bf16 v[90:93], v[164:167], v[188:191], v[90:93]
	v_mfma_f32_16x16x32_bf16 v[82:85], v[142:145], v[196:199], v[82:85]
	v_mfma_f32_16x16x32_bf16 v[74:77], v[164:167], v[196:199], v[74:77]
	v_mfma_f32_16x16x32_bf16 v[126:129], v[160:163], v[176:179], v[126:129]
	v_mfma_f32_16x16x32_bf16 v[122:125], v[168:171], v[176:179], v[122:125]
	v_mfma_f32_16x16x32_bf16 v[118:121], v[160:163], v[184:187], v[118:121]
	v_mfma_f32_16x16x32_bf16 v[106:109], v[168:171], v[184:187], v[106:109]
	v_mfma_f32_16x16x32_bf16 v[98:101], v[160:163], v[192:195], v[98:101]
	v_mfma_f32_16x16x32_bf16 v[90:93], v[168:171], v[192:195], v[90:93]
	v_mfma_f32_16x16x32_bf16 v[82:85], v[160:163], v[200:203], v[82:85]
	s_barrier
	v_mfma_f32_16x16x32_bf16 v[74:77], v[168:171], v[200:203], v[74:77]
	s_setprio 0
	s_add_i32 s18, 0, 0x1c000
	s_add_i32 s19, s38, s20
	v_add_u32_e32 v159, s18, v154
	v_lshl_add_u64 v[210:211], v[210:211], 0, s[10:11]
	s_mov_b32 m0, s19
	ds_read_b128 v[204:207], v159
	ds_read_b128 v[214:217], v159 offset:1024
	ds_read_b128 v[218:221], v159 offset:2048
	ds_read_b128 v[222:225], v159 offset:3072
	global_load_lds_dwordx4 v[210:211], off
	v_lshl_add_u64 v[210:211], v[226:227], 0, s[10:11]
	s_add_i32 m0, s19, 0x2000
	s_nop 0
	global_load_lds_dwordx4 v[210:211], off
	s_barrier
	s_waitcnt lgkmcnt(0)
	s_setprio 1
	s_waitcnt lgkmcnt(0)
	v_mfma_f32_16x16x32_bf16 v[114:117], v[204:207], v[172:175], v[114:117]
	v_mfma_f32_16x16x32_bf16 v[110:113], v[218:221], v[172:175], v[110:113]
	v_mfma_f32_16x16x32_bf16 v[102:105], v[204:207], v[180:183], v[102:105]
	v_mfma_f32_16x16x32_bf16 v[94:97], v[218:221], v[180:183], v[94:97]
	v_mfma_f32_16x16x32_bf16 v[86:89], v[204:207], v[188:191], v[86:89]
	v_mfma_f32_16x16x32_bf16 v[78:81], v[218:221], v[188:191], v[78:81]
	v_mfma_f32_16x16x32_bf16 v[70:73], v[204:207], v[196:199], v[70:73]
	v_mfma_f32_16x16x32_bf16 v[66:69], v[218:221], v[196:199], v[66:69]
	v_mfma_f32_16x16x32_bf16 v[114:117], v[214:217], v[176:179], v[114:117]
	v_mfma_f32_16x16x32_bf16 v[110:113], v[222:225], v[176:179], v[110:113]
	v_mfma_f32_16x16x32_bf16 v[102:105], v[214:217], v[184:187], v[102:105]
	v_mfma_f32_16x16x32_bf16 v[94:97], v[222:225], v[184:187], v[94:97]
	v_mfma_f32_16x16x32_bf16 v[86:89], v[214:217], v[192:195], v[86:89]
	v_mfma_f32_16x16x32_bf16 v[78:81], v[222:225], v[192:195], v[78:81]
	v_mfma_f32_16x16x32_bf16 v[70:73], v[214:217], v[200:203], v[70:73]
	s_barrier
	v_mfma_f32_16x16x32_bf16 v[66:69], v[222:225], v[200:203], v[66:69]
	s_setprio 0
	s_mov_b32 m0, s28
	v_lshl_add_u64 v[210:211], v[228:229], 0, s[10:11]
	ds_read_b128 v[172:175], v157 offset:49152
	ds_read_b128 v[176:179], v157 offset:50176
	ds_read_b128 v[180:183], v157 offset:51200
	ds_read_b128 v[184:187], v157 offset:52224
	ds_read_b128 v[188:191], v157 offset:53248
	ds_read_b128 v[192:195], v157 offset:54272
	ds_read_b128 v[196:199], v157 offset:55296
	ds_read_b128 v[200:203], v157 offset:56320
	global_load_lds_dwordx4 v[210:211], off
	v_lshl_add_u64 v[210:211], v[230:231], 0, s[10:11]
	s_mov_b32 m0, s29
	s_nop 0
	global_load_lds_dwordx4 v[210:211], off
	s_barrier
; #define PG8_STAGE(bufoff, gbase, voff) do { _Pragma("unroll") for (int _i = 0; _i < 2; ++_i) \
;         __builtin_amdgcn_global_load_lds((const unsigned*)((const char*)(gbase) + (voff)[_i]), (LAS unsigned*)(lds + (bufoff) + ldsw + _i * 8192), 16, 0, 0); } while (0)
; #define PG8_LDA(dst, b, h) do { _Pragma("unroll") for (int m = 0; m < 4; ++m) _Pragma("unroll") for (int k = 0; k < 2; ++k) dst[m][k] = *(const LAS bf16x8*)(lds + PG8_SA(b, h) + aoff + m * 2048 + k * 1024); } while (0)
; #define PG8_LDB(dst, b, h) do { _Pragma("unroll") for (int n = 0; n < 2; ++n) _Pragma("unroll") for (int k = 0; k < 2; ++k) dst[n][k] = *(const LAS bf16x8*)(lds + PG8_SB(b, h) + boff + n * 2048 + k * 1024); } while (0)
; #define PG8_WAIT_V(n) asm volatile("s_waitcnt vmcnt(" #n ")" ::: "memory")
; #define PG8_WAIT_L(n) asm volatile("s_waitcnt lgkmcnt(" #n ")" ::: "memory")
; #define PG8_BAR __builtin_amdgcn_s_barrier()
; #define PG8_SCHED __builtin_amdgcn_sched_barrier(0)
; template <class Epi, class Sched>
; __device__ __forceinline__ void gemm_phase(LAS unsigned char* lds, const Gemm g, const Sched S, const Epi E) {
;     ...
;             PG8_LDB(B0, 1, 0); PG8_SCHED; PG8_LDA(At, 1, 0); PG8_STAGE(PG8_SA(0, 1), a2 + hstep, voffA);
;             PG8_WAIT_L(8); PG8_BAR; PG8_WAIT_L(0); PG8_MMA(0, 0, At, B0); PG8_BAR; PG8_SCHED;
;             PG8_LDB(B1, 1, 1); PG8_STAGE(PG8_SB(1, 0), b3, voffB);
;             PG8_BAR; PG8_WAIT_L(0); PG8_MMA(0, 1, At, B1); PG8_BAR;
;             PG8_LDA(At, 1, 1); PG8_STAGE(PG8_SA(1, 0), a3, voffA);
;             PG8_BAR; PG8_WAIT_L(0); PG8_MMA(1, 0, At, B0); PG8_BAR; PG8_SCHED;
;             PG8_STAGE(PG8_SB(1, 1), b3 + hstep, voffB);
;             PG8_WAIT_V(6); PG8_BAR; PG8_MMA(1, 1, At, B1); PG8_BAR;
;     __device__ __forceinline__ void operator()(const f32x4 (&acc)[2][2][4][2], const Unit& u, int wr, int wc, int fr, int fq) const {
;         const int row0 = u.pm * 256 + wr * 64 + fr, col0 = u.pn * 256 + wc * 32 + 4 * fq;
; #pragma unroll
;         for (int ai = 0; ai < 2; ++ai) {
;             u32x2 bv[4][2][2];
; #pragma unroll
;             for (int m = 0; m < 4; ++m) { const int off = (row0 + ai * HALF + m * 16) * DM + col0;
; #pragma unroll
;                 for (int bj = 0; bj < 2; ++bj)
; #pragma unroll
;                     for (int n = 0; n < 2; ++n) bv[m][bj][n] = *(const u32x2*)(base + off + bj * HALF + n * 16); }
	s_waitcnt lgkmcnt(0)
	s_setprio 1
	s_waitcnt lgkmcnt(0)
	v_mfma_f32_16x16x32_bf16 v[62:65], v[142:145], v[172:175], v[62:65]
	v_mfma_f32_16x16x32_bf16 v[58:61], v[164:167], v[172:175], v[58:61]
	v_mfma_f32_16x16x32_bf16 v[50:53], v[142:145], v[180:183], v[50:53]
	v_mfma_f32_16x16x32_bf16 v[42:45], v[164:167], v[180:183], v[42:45]
	v_mfma_f32_16x16x32_bf16 v[34:37], v[142:145], v[188:191], v[34:37]
	v_mfma_f32_16x16x32_bf16 v[26:29], v[164:167], v[188:191], v[26:29]
	v_mfma_f32_16x16x32_bf16 v[18:21], v[142:145], v[196:199], v[18:21]
	v_mfma_f32_16x16x32_bf16 v[10:13], v[164:167], v[196:199], v[10:13]
	v_mfma_f32_16x16x32_bf16 v[62:65], v[160:163], v[176:179], v[62:65]
	v_mfma_f32_16x16x32_bf16 v[58:61], v[168:171], v[176:179], v[58:61]
	v_mfma_f32_16x16x32_bf16 v[50:53], v[160:163], v[184:187], v[50:53]
	v_mfma_f32_16x16x32_bf16 v[42:45], v[168:171], v[184:187], v[42:45]
	v_mfma_f32_16x16x32_bf16 v[34:37], v[160:163], v[192:195], v[34:37]
	v_mfma_f32_16x16x32_bf16 v[26:29], v[168:171], v[192:195], v[26:29]
	v_mfma_f32_16x16x32_bf16 v[18:21], v[160:163], v[200:203], v[18:21]
	s_barrier
	v_mfma_f32_16x16x32_bf16 v[10:13], v[168:171], v[200:203], v[10:13]
	s_setprio 0
	s_add_u32 s16, s16, 0x160080
	s_addc_u32 s17, s17, 0
	s_add_i32 s18, s18, s20
	v_lshl_add_u64 v[142:143], s[16:17], 0, v[130:131]
	s_mov_b32 m0, s18
	s_nop 0
	global_load_lds_dwordx4 v[142:143], off
	v_lshl_add_u64 v[142:143], s[16:17], 0, v[132:133]
	s_add_i32 m0, s18, 0x2000
	s_nop 0
	global_load_lds_dwordx4 v[142:143], off
	s_waitcnt vmcnt(6)
	s_barrier
	s_setprio 1
	v_mfma_f32_16x16x32_bf16 v[54:57], v[204:207], v[172:175], v[54:57]
	v_mfma_f32_16x16x32_bf16 v[46:49], v[218:221], v[172:175], v[46:49]
	v_mfma_f32_16x16x32_bf16 v[38:41], v[204:207], v[180:183], v[38:41]
	v_mfma_f32_16x16x32_bf16 v[30:33], v[218:221], v[180:183], v[30:33]
	v_mfma_f32_16x16x32_bf16 v[22:25], v[204:207], v[188:191], v[22:25]
	v_mfma_f32_16x16x32_bf16 v[14:17], v[218:221], v[188:191], v[14:17]
	v_mfma_f32_16x16x32_bf16 v[6:9], v[204:207], v[196:199], v[6:9]
	v_mfma_f32_16x16x32_bf16 v[2:5], v[218:221], v[196:199], v[2:5]
	v_mfma_f32_16x16x32_bf16 v[54:57], v[214:217], v[176:179], v[54:57]
	v_mfma_f32_16x16x32_bf16 v[46:49], v[222:225], v[176:179], v[46:49]
	v_mfma_f32_16x16x32_bf16 v[38:41], v[214:217], v[184:187], v[38:41]
	v_mfma_f32_16x16x32_bf16 v[30:33], v[222:225], v[184:187], v[30:33]
	v_mfma_f32_16x16x32_bf16 v[22:25], v[214:217], v[192:195], v[22:25]
	v_mfma_f32_16x16x32_bf16 v[14:17], v[222:225], v[192:195], v[14:17]
	v_mfma_f32_16x16x32_bf16 v[6:9], v[214:217], v[200:203], v[6:9]
	s_barrier
	v_mfma_f32_16x16x32_bf16 v[2:5], v[222:225], v[200:203], v[2:5]
	s_setprio 0
	s_add_i32 s37, s37, 2
	s_add_u32 s12, s12, 0x100
	s_addc_u32 s13, s13, 0
	s_add_u32 s14, s14, 0x100
	s_addc_u32 s15, s15, 0
	s_cmpk_gt_u32 s37, 0x55
	s_cbranch_scc0 .LBB0_1598
	s_lshl_b32 s2, s2, 8
	s_lshl_b32 s12, s36, 19
	s_add_i32 s12, s12, s2
	v_add_u32_e32 v142, s12, v155
	v_ashrrev_i32_e32 v143, 31, v142
	v_lshlrev_b64 v[160:161], 1, v[142:143]
	v_lshl_add_u64 v[144:145], s[74:75], 0, v[160:161]
	global_load_dwordx2 v[162:163], v[144:145], off
	global_load_dwordx2 v[164:165], v[144:145], off offset:32
	global_load_dwordx2 v[166:167], v[144:145], off offset:256
	global_load_dwordx2 v[168:169], v[144:145], off offset:288
	v_add_u32_e32 v144, 0x8000, v142
	v_ashrrev_i32_e32 v145, 31, v144
	v_lshlrev_b64 v[170:171], 1, v[144:145]
	v_lshl_add_u64 v[172:173], s[74:75], 0, v[170:171]
	global_load_dwordx2 v[174:175], v[172:173], off
	global_load_dwordx2 v[176:177], v[172:173], off offset:32
	v_add_u32_e32 v144, 0x10000, v142
	v_add_u32_e32 v178, 0x18000, v142
	v_ashrrev_i32_e32 v145, 31, v144
	v_ashrrev_i32_e32 v179, 31, v178
	v_lshlrev_b64 v[180:181], 1, v[144:145]
	v_lshlrev_b64 v[144:145], 1, v[178:179]
	global_load_dwordx2 v[178:179], v[172:173], off offset:256
	v_lshl_add_u64 v[182:183], s[74:75], 0, v[180:181]
	v_lshl_add_u64 v[184:185], s[74:75], 0, v[144:145]
	global_load_dwordx2 v[172:173], v[172:173], off offset:288
	s_nop 0
	global_load_dwordx2 v[186:187], v[182:183], off
	global_load_dwordx2 v[188:189], v[182:183], off offset:32
	global_load_dwordx2 v[190:191], v[182:183], off offset:256
	s_nop 0
	global_load_dwordx2 v[182:183], v[182:183], off offset:288
	s_nop 0
	global_load_dwordx2 v[192:193], v[184:185], off
	global_load_dwordx2 v[194:195], v[184:185], off offset:32
	global_load_dwordx2 v[196:197], v[184:185], off offset:256
	s_nop 0
	global_load_dwordx2 v[184:185], v[184:185], off offset:288
	v_lshl_add_u64 v[160:161], s[84:85], 0, v[160:161]
	v_lshl_add_u64 v[170:171], s[84:85], 0, v[170:171]
	s_and_b64 vcc, exec, s[4:5]
	s_mov_b32 s2, s34
	s_mov_b32 s36, s35
	s_mov_b64 s[16:17], s[0:1]
	s_mov_b64 s[12:13], s[6:7]
	v_add_u32_e32 v248, 0x40000, v142
	v_ashrrev_i32_e32 v249, 31, v248
	v_lshl_add_u64 v[248:249], v[248:249], 1, s[74:75]
	v_add_u32_e32 v250, 0x48000, v142
	v_ashrrev_i32_e32 v251, 31, v250
	v_lshl_add_u64 v[250:251], v[250:251], 1, s[74:75]
	v_add_u32_e32 v252, 0x50000, v142
	v_ashrrev_i32_e32 v253, 31, v252
	v_lshl_add_u64 v[252:253], v[252:253], 1, s[74:75]
	v_add_u32_e32 v254, 0x58000, v142
	v_ashrrev_i32_e32 v255, 31, v254
	v_lshl_add_u64 v[254:255], v[254:255], 1, s[74:75]
	global_load_dwordx2 v[214:215], v[248:249], off
	global_load_dwordx2 v[216:217], v[248:249], off offset:32
	global_load_dwordx2 v[218:219], v[248:249], off offset:256
	global_load_dwordx2 v[220:221], v[248:249], off offset:288
	global_load_dwordx2 v[222:223], v[250:251], off
	global_load_dwordx2 v[224:225], v[250:251], off offset:32
	global_load_dwordx2 v[226:227], v[250:251], off offset:256
	global_load_dwordx2 v[228:229], v[250:251], off offset:288
	global_load_dwordx2 v[230:231], v[252:253], off
	global_load_dwordx2 v[232:233], v[252:253], off offset:32
	global_load_dwordx2 v[234:235], v[252:253], off offset:256
	global_load_dwordx2 v[236:237], v[252:253], off offset:288
	global_load_dwordx2 v[238:239], v[254:255], off
	global_load_dwordx2 v[240:241], v[254:255], off offset:32
	global_load_dwordx2 v[242:243], v[254:255], off offset:256
	global_load_dwordx2 v[246:247], v[254:255], off offset:288
	s_waitcnt vmcnt(16)
; __device__ __forceinline__ unsigned cvtpk(float lo, float hi) { unsigned r; asm volatile("v_cvt_pk_bf16_f32 %0, %1, %2" : "=v"(r) : "v"(lo), "v"(hi)); return r; }
;     __device__ __forceinline__ void operator()(const f32x4 (&acc)[2][2][4][2], const Unit& u, int wr, int wc, int fr, int fq) const {
;     ...
;             for (int m = 0; m < 4; ++m) { const int off = (row0 + ai * HALF + m * 16) * DM + col0;
; #pragma unroll
;                 for (int bj = 0; bj < 2; ++bj)
; #pragma unroll
;                     for (int n = 0; n < 2; ++n) { const u32x2 b = bv[m][bj][n]; const f32x4 a4 = acc[ai][bj][m][n];
;                         const float v0 = __uint_as_float(b.x << 16) + a4[0] * s, v1 = __uint_as_float(b.x & 0xffff0000u) + a4[1] * s, v2 = __uint_as_float(b.y << 16) + a4[2] * s, v3 = __uint_as_float(b.y & 0xffff0000u) + a4[3] * s;
;                         u32x2 w; w.x = cvtpk(v0, v1); w.y = cvtpk(v2, v3); *(u32x2*)(xb + off + bj * HALF + n * 16) = w; } }
	v_lshlrev_b32_e32 v143, 16, v162
	v_and_b32_e32 v159, 0xffff0000, v162
	v_lshlrev_b32_e32 v162, 16, v163
	v_and_b32_e32 v163, 0xffff0000, v163
	v_lshlrev_b32_e32 v202, 16, v168
	v_and_b32_e32 v168, 0xffff0000, v168
	v_lshlrev_b32_e32 v198, 16, v164
	v_and_b32_e32 v164, 0xffff0000, v164
	v_lshlrev_b32_e32 v199, 16, v165
	v_and_b32_e32 v165, 0xffff0000, v165
	v_lshlrev_b32_e32 v201, 16, v167
	v_fmac_f32_e32 v143, 0.5, v126
	v_fmac_f32_e32 v159, 0.5, v127
	v_fmac_f32_e32 v162, 0.5, v128
	v_fmac_f32_e32 v163, 0.5, v129
	v_fmac_f32_e32 v202, 0.5, v110
	v_fmac_f32_e32 v168, 0.5, v111
	v_cvt_pk_bf16_f32 v110, v143, v159
	v_cvt_pk_bf16_f32 v111, v162, v163
	v_lshlrev_b32_e32 v200, 16, v166
	v_and_b32_e32 v166, 0xffff0000, v166
	v_and_b32_e32 v167, 0xffff0000, v167
	v_fmac_f32_e32 v198, 0.5, v122
	v_fmac_f32_e32 v164, 0.5, v123
	v_fmac_f32_e32 v199, 0.5, v124
	v_fmac_f32_e32 v165, 0.5, v125
	v_fmac_f32_e32 v201, 0.5, v116
	v_lshlrev_b32_e32 v116, 16, v176
	global_store_dwordx2 v[160:161], v[110:111], off
	v_cvt_pk_bf16_f32 v110, v198, v164
	v_cvt_pk_bf16_f32 v111, v199, v165
	v_lshlrev_b32_e32 v203, 16, v169
	v_and_b32_e32 v169, 0xffff0000, v169
	v_fmac_f32_e32 v200, 0.5, v114
	v_fmac_f32_e32 v166, 0.5, v115
	v_fmac_f32_e32 v167, 0.5, v117
	v_fmac_f32_e32 v116, 0.5, v106
	global_store_dwordx2 v[160:161], v[110:111], off offset:32
	v_cvt_pk_bf16_f32 v110, v200, v166
	v_cvt_pk_bf16_f32 v111, v201, v167
	v_and_b32_e32 v106, 0xffff0000, v176
	v_fmac_f32_e32 v203, 0.5, v112
	v_fmac_f32_e32 v169, 0.5, v113
	v_lshlrev_b32_e32 v112, 16, v174
	v_and_b32_e32 v113, 0xffff0000, v174
	v_lshlrev_b32_e32 v114, 16, v175
	v_and_b32_e32 v115, 0xffff0000, v175
	global_store_dwordx2 v[160:161], v[110:111], off offset:256
	v_cvt_pk_bf16_f32 v110, v202, v168
	v_cvt_pk_bf16_f32 v111, v203, v169
	v_fmac_f32_e32 v106, 0.5, v107
	v_lshlrev_b32_e32 v107, 16, v177
	v_fmac_f32_e32 v112, 0.5, v118
	v_fmac_f32_e32 v113, 0.5, v119
	v_fmac_f32_e32 v114, 0.5, v120
	v_fmac_f32_e32 v115, 0.5, v121
	global_store_dwordx2 v[160:161], v[110:111], off offset:288
	v_cvt_pk_bf16_f32 v110, v112, v113
	v_cvt_pk_bf16_f32 v111, v114, v115
	global_store_dwordx2 v[170:171], v[110:111], off
	v_fmac_f32_e32 v107, 0.5, v108
	v_and_b32_e32 v108, 0xffff0000, v177
	v_cvt_pk_bf16_f32 v106, v116, v106
	v_fmac_f32_e32 v108, 0.5, v109
	v_cvt_pk_bf16_f32 v107, v107, v108
	global_store_dwordx2 v[170:171], v[106:107], off offset:32
	v_lshlrev_b32_e32 v106, 16, v178
	v_fmac_f32_e32 v106, 0.5, v102
	v_and_b32_e32 v102, 0xffff0000, v178
	v_fmac_f32_e32 v102, 0.5, v103
	v_lshlrev_b32_e32 v103, 16, v179
	v_fmac_f32_e32 v103, 0.5, v104
	v_and_b32_e32 v104, 0xffff0000, v179
	v_cvt_pk_bf16_f32 v102, v106, v102
	v_fmac_f32_e32 v104, 0.5, v105
	v_cvt_pk_bf16_f32 v103, v103, v104
	global_store_dwordx2 v[170:171], v[102:103], off offset:256
	v_lshlrev_b32_e32 v102, 16, v172
	v_fmac_f32_e32 v102, 0.5, v94
	v_and_b32_e32 v94, 0xffff0000, v172
	v_fmac_f32_e32 v94, 0.5, v95
	v_lshlrev_b32_e32 v95, 16, v173
	v_fmac_f32_e32 v95, 0.5, v96
	v_and_b32_e32 v96, 0xffff0000, v173
	v_fmac_f32_e32 v96, 0.5, v97
	v_cvt_pk_bf16_f32 v94, v102, v94
	v_cvt_pk_bf16_f32 v95, v95, v96
	global_store_dwordx2 v[170:171], v[94:95], off offset:288
	v_lshlrev_b32_e32 v94, 16, v186
	v_and_b32_e32 v95, 0xffff0000, v186
	v_lshlrev_b32_e32 v96, 16, v187
	v_and_b32_e32 v97, 0xffff0000, v187
	v_fmac_f32_e32 v94, 0.5, v98
	v_fmac_f32_e32 v95, 0.5, v99
	v_fmac_f32_e32 v96, 0.5, v100
	v_fmac_f32_e32 v97, 0.5, v101
	v_cvt_pk_bf16_f32 v94, v94, v95
	v_cvt_pk_bf16_f32 v95, v96, v97
	v_lshl_add_u64 v[96:97], s[84:85], 0, v[180:181]
	global_store_dwordx2 v[96:97], v[94:95], off
	v_lshlrev_b32_e32 v94, 16, v188
	v_fmac_f32_e32 v94, 0.5, v90
	v_and_b32_e32 v90, 0xffff0000, v188
	v_fmac_f32_e32 v90, 0.5, v91
	v_lshlrev_b32_e32 v91, 16, v189
	v_fmac_f32_e32 v91, 0.5, v92
	v_and_b32_e32 v92, 0xffff0000, v189
	v_cvt_pk_bf16_f32 v90, v94, v90
	v_fmac_f32_e32 v92, 0.5, v93
	v_cvt_pk_bf16_f32 v91, v91, v92
	global_store_dwordx2 v[96:97], v[90:91], off offset:32
	v_lshlrev_b32_e32 v90, 16, v190
	v_fmac_f32_e32 v90, 0.5, v86
	v_and_b32_e32 v86, 0xffff0000, v190
	v_fmac_f32_e32 v86, 0.5, v87
	v_lshlrev_b32_e32 v87, 16, v191
	v_fmac_f32_e32 v87, 0.5, v88
	v_and_b32_e32 v88, 0xffff0000, v191
	v_cvt_pk_bf16_f32 v86, v90, v86
	v_fmac_f32_e32 v88, 0.5, v89
	v_cvt_pk_bf16_f32 v87, v87, v88
	global_store_dwordx2 v[96:97], v[86:87], off offset:256
	v_lshlrev_b32_e32 v86, 16, v182
	v_fmac_f32_e32 v86, 0.5, v78
	v_and_b32_e32 v78, 0xffff0000, v182
	v_fmac_f32_e32 v78, 0.5, v79
	v_lshlrev_b32_e32 v79, 16, v183
	v_fmac_f32_e32 v79, 0.5, v80
	v_and_b32_e32 v80, 0xffff0000, v183
	v_fmac_f32_e32 v80, 0.5, v81
	v_cvt_pk_bf16_f32 v78, v86, v78
	v_cvt_pk_bf16_f32 v79, v79, v80
	global_store_dwordx2 v[96:97], v[78:79], off offset:288
	v_lshlrev_b32_e32 v78, 16, v192
	v_and_b32_e32 v79, 0xffff0000, v192
	v_lshlrev_b32_e32 v80, 16, v193
	v_and_b32_e32 v81, 0xffff0000, v193
	v_fmac_f32_e32 v78, 0.5, v82
	v_fmac_f32_e32 v79, 0.5, v83
	v_fmac_f32_e32 v80, 0.5, v84
	v_fmac_f32_e32 v81, 0.5, v85
	v_cvt_pk_bf16_f32 v78, v78, v79
	v_cvt_pk_bf16_f32 v79, v80, v81
	v_lshl_add_u64 v[80:81], s[84:85], 0, v[144:145]
	global_store_dwordx2 v[80:81], v[78:79], off
	v_lshlrev_b32_e32 v78, 16, v194
	v_fmac_f32_e32 v78, 0.5, v74
	v_and_b32_e32 v74, 0xffff0000, v194
	v_fmac_f32_e32 v74, 0.5, v75
	v_lshlrev_b32_e32 v75, 16, v195
	v_fmac_f32_e32 v75, 0.5, v76
	v_and_b32_e32 v76, 0xffff0000, v195
	v_cvt_pk_bf16_f32 v74, v78, v74
	v_fmac_f32_e32 v76, 0.5, v77
	v_cvt_pk_bf16_f32 v75, v75, v76
	global_store_dwordx2 v[80:81], v[74:75], off offset:32
	v_lshlrev_b32_e32 v74, 16, v196
	v_fmac_f32_e32 v74, 0.5, v70
	v_and_b32_e32 v70, 0xffff0000, v196
	v_fmac_f32_e32 v70, 0.5, v71
	v_lshlrev_b32_e32 v71, 16, v197
	v_fmac_f32_e32 v71, 0.5, v72
	v_and_b32_e32 v72, 0xffff0000, v197
	v_cvt_pk_bf16_f32 v70, v74, v70
	v_fmac_f32_e32 v72, 0.5, v73
	v_cvt_pk_bf16_f32 v71, v71, v72
	global_store_dwordx2 v[80:81], v[70:71], off offset:256
	v_lshlrev_b32_e32 v70, 16, v184
	v_fmac_f32_e32 v70, 0.5, v66
	v_and_b32_e32 v66, 0xffff0000, v184
	v_fmac_f32_e32 v66, 0.5, v67
	v_lshlrev_b32_e32 v67, 16, v185
	v_fmac_f32_e32 v67, 0.5, v68
	v_and_b32_e32 v68, 0xffff0000, v185
	v_cvt_pk_bf16_f32 v66, v70, v66
	v_fmac_f32_e32 v68, 0.5, v69
	v_cvt_pk_bf16_f32 v67, v67, v68
	global_store_dwordx2 v[80:81], v[66:67], off offset:288
	v_add_u32_e32 v66, 0x40000, v142
	v_ashrrev_i32_e32 v67, 31, v66
	v_lshlrev_b64 v[68:69], 1, v[66:67]
	v_lshl_add_u64 v[66:67], s[74:75], 0, v[68:69]
	v_add_u32_e32 v66, 0x48000, v142
	v_ashrrev_i32_e32 v67, 31, v66
	v_lshlrev_b64 v[78:79], 1, v[66:67]
	v_lshl_add_u64 v[66:67], s[74:75], 0, v[78:79]
	v_add_u32_e32 v66, 0x50000, v142
	v_ashrrev_i32_e32 v67, 31, v66
	v_lshlrev_b64 v[88:89], 1, v[66:67]
	v_lshl_add_u64 v[66:67], s[74:75], 0, v[88:89]
	v_add_u32_e32 v66, 0x58000, v142
	v_ashrrev_i32_e32 v67, 31, v66
	v_lshlrev_b64 v[98:99], 1, v[66:67]
	v_lshl_add_u64 v[66:67], s[74:75], 0, v[98:99]
	s_nop 0
	s_waitcnt vmcnt(16)
; __device__ __forceinline__ unsigned cvtpk(float lo, float hi) { unsigned r; asm volatile("v_cvt_pk_bf16_f32 %0, %1, %2" : "=v"(r) : "v"(lo), "v"(hi)); return r; }
;     __device__ __forceinline__ void operator()(const f32x4 (&acc)[2][2][4][2], const Unit& u, int wr, int wc, int fr, int fq) const {
;     ...
;             for (int m = 0; m < 4; ++m) { const int off = (row0 + ai * HALF + m * 16) * DM + col0;
; #pragma unroll
;                 for (int bj = 0; bj < 2; ++bj)
; #pragma unroll
;                     for (int n = 0; n < 2; ++n) { const u32x2 b = bv[m][bj][n]; const f32x4 a4 = acc[ai][bj][m][n];
;                         const float v0 = __uint_as_float(b.x << 16) + a4[0] * s, v1 = __uint_as_float(b.x & 0xffff0000u) + a4[1] * s, v2 = __uint_as_float(b.y << 16) + a4[2] * s, v3 = __uint_as_float(b.y & 0xffff0000u) + a4[3] * s;
;                         u32x2 w; w.x = cvtpk(v0, v1); w.y = cvtpk(v2, v3); *(u32x2*)(xb + off + bj * HALF + n * 16) = w; } }
	v_lshlrev_b32_e32 v106, 16, v214
	v_fmac_f32_e32 v106, 0.5, v62
	v_and_b32_e32 v62, 0xffff0000, v214
	v_fmac_f32_e32 v62, 0.5, v63
	v_lshlrev_b32_e32 v63, 16, v215
	v_fmac_f32_e32 v63, 0.5, v64
	v_and_b32_e32 v64, 0xffff0000, v215
	v_fmac_f32_e32 v64, 0.5, v65
	v_cvt_pk_bf16_f32 v62, v106, v62
	v_cvt_pk_bf16_f32 v63, v63, v64
	v_lshl_add_u64 v[64:65], s[84:85], 0, v[68:69]
	global_store_dwordx2 v[64:65], v[62:63], off
	v_lshlrev_b32_e32 v62, 16, v216
	v_fmac_f32_e32 v62, 0.5, v58
	v_and_b32_e32 v58, 0xffff0000, v216
	v_fmac_f32_e32 v58, 0.5, v59
	v_lshlrev_b32_e32 v59, 16, v217
	v_fmac_f32_e32 v59, 0.5, v60
	v_and_b32_e32 v60, 0xffff0000, v217
	v_cvt_pk_bf16_f32 v58, v62, v58
	v_fmac_f32_e32 v60, 0.5, v61
	v_cvt_pk_bf16_f32 v59, v59, v60
	global_store_dwordx2 v[64:65], v[58:59], off offset:32
	v_lshlrev_b32_e32 v58, 16, v218
	v_fmac_f32_e32 v58, 0.5, v54
	v_and_b32_e32 v54, 0xffff0000, v218
	v_fmac_f32_e32 v54, 0.5, v55
	v_lshlrev_b32_e32 v55, 16, v219
	v_fmac_f32_e32 v55, 0.5, v56
	v_and_b32_e32 v56, 0xffff0000, v219
	v_cvt_pk_bf16_f32 v54, v58, v54
	v_fmac_f32_e32 v56, 0.5, v57
	v_cvt_pk_bf16_f32 v55, v55, v56
	global_store_dwordx2 v[64:65], v[54:55], off offset:256
	v_lshlrev_b32_e32 v54, 16, v220
	v_fmac_f32_e32 v54, 0.5, v46
	v_and_b32_e32 v46, 0xffff0000, v220
	v_fmac_f32_e32 v46, 0.5, v47
	v_lshlrev_b32_e32 v47, 16, v221
	v_fmac_f32_e32 v47, 0.5, v48
	v_and_b32_e32 v48, 0xffff0000, v221
	v_fmac_f32_e32 v48, 0.5, v49
	v_cvt_pk_bf16_f32 v46, v54, v46
	v_cvt_pk_bf16_f32 v47, v47, v48
	global_store_dwordx2 v[64:65], v[46:47], off offset:288
	v_lshlrev_b32_e32 v46, 16, v222
	v_and_b32_e32 v47, 0xffff0000, v222
	v_lshlrev_b32_e32 v48, 16, v223
	v_and_b32_e32 v49, 0xffff0000, v223
	v_fmac_f32_e32 v46, 0.5, v50
	v_fmac_f32_e32 v47, 0.5, v51
	v_fmac_f32_e32 v48, 0.5, v52
	v_fmac_f32_e32 v49, 0.5, v53
	v_cvt_pk_bf16_f32 v46, v46, v47
	v_cvt_pk_bf16_f32 v47, v48, v49
	v_lshl_add_u64 v[48:49], s[84:85], 0, v[78:79]
	global_store_dwordx2 v[48:49], v[46:47], off
	v_lshlrev_b32_e32 v46, 16, v224
	v_fmac_f32_e32 v46, 0.5, v42
	v_and_b32_e32 v42, 0xffff0000, v224
	v_fmac_f32_e32 v42, 0.5, v43
	v_lshlrev_b32_e32 v43, 16, v225
	v_fmac_f32_e32 v43, 0.5, v44
	v_and_b32_e32 v44, 0xffff0000, v225
	v_cvt_pk_bf16_f32 v42, v46, v42
	v_fmac_f32_e32 v44, 0.5, v45
	v_cvt_pk_bf16_f32 v43, v43, v44
	global_store_dwordx2 v[48:49], v[42:43], off offset:32
	v_lshlrev_b32_e32 v42, 16, v226
	v_fmac_f32_e32 v42, 0.5, v38
	v_and_b32_e32 v38, 0xffff0000, v226
	v_fmac_f32_e32 v38, 0.5, v39
	v_lshlrev_b32_e32 v39, 16, v227
	v_fmac_f32_e32 v39, 0.5, v40
	v_and_b32_e32 v40, 0xffff0000, v227
	v_cvt_pk_bf16_f32 v38, v42, v38
	v_fmac_f32_e32 v40, 0.5, v41
	v_cvt_pk_bf16_f32 v39, v39, v40
	global_store_dwordx2 v[48:49], v[38:39], off offset:256
	v_lshlrev_b32_e32 v38, 16, v228
	v_fmac_f32_e32 v38, 0.5, v30
	v_and_b32_e32 v30, 0xffff0000, v228
	v_fmac_f32_e32 v30, 0.5, v31
	v_lshlrev_b32_e32 v31, 16, v229
	v_fmac_f32_e32 v31, 0.5, v32
	v_and_b32_e32 v32, 0xffff0000, v229
	v_fmac_f32_e32 v32, 0.5, v33
	v_cvt_pk_bf16_f32 v30, v38, v30
	v_cvt_pk_bf16_f32 v31, v31, v32
	global_store_dwordx2 v[48:49], v[30:31], off offset:288
	v_lshlrev_b32_e32 v30, 16, v230
	v_and_b32_e32 v31, 0xffff0000, v230
	v_lshlrev_b32_e32 v32, 16, v231
	v_and_b32_e32 v33, 0xffff0000, v231
	v_fmac_f32_e32 v30, 0.5, v34
	v_fmac_f32_e32 v31, 0.5, v35
	v_fmac_f32_e32 v32, 0.5, v36
	v_fmac_f32_e32 v33, 0.5, v37
	v_cvt_pk_bf16_f32 v30, v30, v31
	v_cvt_pk_bf16_f32 v31, v32, v33
	v_lshl_add_u64 v[32:33], s[84:85], 0, v[88:89]
	global_store_dwordx2 v[32:33], v[30:31], off
	v_lshlrev_b32_e32 v30, 16, v232
	v_fmac_f32_e32 v30, 0.5, v26
	v_and_b32_e32 v26, 0xffff0000, v232
	v_fmac_f32_e32 v26, 0.5, v27
	v_lshlrev_b32_e32 v27, 16, v233
	v_fmac_f32_e32 v27, 0.5, v28
	v_and_b32_e32 v28, 0xffff0000, v233
	v_cvt_pk_bf16_f32 v26, v30, v26
	v_fmac_f32_e32 v28, 0.5, v29
	v_cvt_pk_bf16_f32 v27, v27, v28
	global_store_dwordx2 v[32:33], v[26:27], off offset:32
	v_lshlrev_b32_e32 v26, 16, v234
	v_fmac_f32_e32 v26, 0.5, v22
	v_and_b32_e32 v22, 0xffff0000, v234
	v_fmac_f32_e32 v22, 0.5, v23
	v_lshlrev_b32_e32 v23, 16, v235
	v_fmac_f32_e32 v23, 0.5, v24
	v_and_b32_e32 v24, 0xffff0000, v235
	v_cvt_pk_bf16_f32 v22, v26, v22
	v_fmac_f32_e32 v24, 0.5, v25
	v_cvt_pk_bf16_f32 v23, v23, v24
	global_store_dwordx2 v[32:33], v[22:23], off offset:256
	v_lshlrev_b32_e32 v22, 16, v236
	v_fmac_f32_e32 v22, 0.5, v14
	v_and_b32_e32 v14, 0xffff0000, v236
	v_fmac_f32_e32 v14, 0.5, v15
	v_lshlrev_b32_e32 v15, 16, v237
	v_fmac_f32_e32 v15, 0.5, v16
	v_and_b32_e32 v16, 0xffff0000, v237
	v_fmac_f32_e32 v16, 0.5, v17
	v_cvt_pk_bf16_f32 v14, v22, v14
	v_cvt_pk_bf16_f32 v15, v15, v16
	global_store_dwordx2 v[32:33], v[14:15], off offset:288
	v_lshlrev_b32_e32 v14, 16, v238
	v_and_b32_e32 v15, 0xffff0000, v238
	v_lshlrev_b32_e32 v16, 16, v239
	v_and_b32_e32 v17, 0xffff0000, v239
	v_fmac_f32_e32 v14, 0.5, v18
	v_fmac_f32_e32 v15, 0.5, v19
	v_fmac_f32_e32 v16, 0.5, v20
	v_fmac_f32_e32 v17, 0.5, v21
	v_cvt_pk_bf16_f32 v14, v14, v15
	v_cvt_pk_bf16_f32 v15, v16, v17
	v_lshl_add_u64 v[16:17], s[84:85], 0, v[98:99]
	global_store_dwordx2 v[16:17], v[14:15], off
	v_lshlrev_b32_e32 v14, 16, v240
	v_fmac_f32_e32 v14, 0.5, v10
	v_and_b32_e32 v10, 0xffff0000, v240
	v_fmac_f32_e32 v10, 0.5, v11
	v_lshlrev_b32_e32 v11, 16, v241
	v_fmac_f32_e32 v11, 0.5, v12
	v_and_b32_e32 v12, 0xffff0000, v241
	v_cvt_pk_bf16_f32 v10, v14, v10
	v_fmac_f32_e32 v12, 0.5, v13
	v_cvt_pk_bf16_f32 v11, v11, v12
	global_store_dwordx2 v[16:17], v[10:11], off offset:32
	v_lshlrev_b32_e32 v10, 16, v242
	v_fmac_f32_e32 v10, 0.5, v6
	v_and_b32_e32 v6, 0xffff0000, v242
	v_fmac_f32_e32 v6, 0.5, v7
	v_lshlrev_b32_e32 v7, 16, v243
	v_fmac_f32_e32 v7, 0.5, v8
	v_and_b32_e32 v8, 0xffff0000, v243
	v_cvt_pk_bf16_f32 v6, v10, v6
	v_fmac_f32_e32 v8, 0.5, v9
	v_cvt_pk_bf16_f32 v7, v7, v8
	global_store_dwordx2 v[16:17], v[6:7], off offset:256
	v_lshlrev_b32_e32 v6, 16, v246
	v_fmac_f32_e32 v6, 0.5, v2
	v_and_b32_e32 v2, 0xffff0000, v246
	v_fmac_f32_e32 v2, 0.5, v3
	v_lshlrev_b32_e32 v3, 16, v247
	v_fmac_f32_e32 v3, 0.5, v4
	v_and_b32_e32 v4, 0xffff0000, v247
	v_fmac_f32_e32 v4, 0.5, v5
	v_cvt_pk_bf16_f32 v2, v6, v2
	v_cvt_pk_bf16_f32 v3, v3, v4
	global_store_dwordx2 v[16:17], v[2:3], off offset:288
	s_cbranch_vccz .LBB0_1587
	s_waitcnt vmcnt(0)
	s_cmpk_gt_u32 s3, 0xff
	s_cbranch_scc1 .LBB0_1602
	s_barrier
